# first K-loop iteration peeled in 5 GEMM loops: first MFMA per accumulator uses C=0, 128 zeroing v_mov per tile removed
# speedup vs baseline: 1.0187x; 1.0187x over previous
;     __device__ __forceinline__ const char* tile(const Unit& u, int t) const { return A + (size_t)u.pm * 2 * hstep() + (size_t)t * (BK * 2); }
;     __device__ __forceinline__ const char* tile(const Unit& u, int t) const { return U + (long)(t >> 2) * xoff + (size_t)u.pn * (1024 * 512) + (size_t)u.pm * 2 * hstep() + (size_t)(t & 3) * (BK * 2); }
;     ...
;     AccT acc;
; #pragma unroll
;     for (int a = 0; a < 2; ++a)
; #pragma unroll
;         for (int b = 0; b < 2; ++b)
; #pragma unroll
;             for (int m = 0; m < 4; ++m)
; #pragma unroll
;                 for (int n = 0; n < 2; ++n) acc[a][b][m][n] = (f32x4){0.f, 0.f, 0.f, 0.f};
;     bf16x8 At[4][2], B0[2][2], B1[2][2];
;     const char* cB = (const char*)g.Bt + (size_t)cur.pn * 2 * hstepB;
;     { const char* cA0 = AS.tile(cur, 0); const char* cA1 = AS.tile(cur, 1);
;       PG8_STAGE(PG8_SB(0, 0), cB, voffB); PG8_STAGE(PG8_SB(0, 1), cB + hstepB, voffB); PG8_STAGE(PG8_SA(0, 0), cA0, voffA); PG8_STAGE(PG8_SA(0, 1), cA0 + hstepA, voffA);
;       PG8_STAGE(PG8_SB(1, 0), cB + kstep, voffB); PG8_STAGE(PG8_SA(1, 0), cA1, voffA); PG8_STAGE(PG8_SB(1, 1), cB + hstepB + kstep, voffB);
;       E.prologue(cur, lds, tid);
;       if (wr == 1) PG8_BAR;
;       PG8_WAIT_V(8); PG8_BAR;
;       PG8_WAIT_V(6); PG8_BAR; }
;     for (;;) {
;         const bool has_next = S.next(ui + 1, nxt);
;         const Unit nu = has_next ? nxt : cur;
;         const char* nB = (const char*)g.Bt + (size_t)nu.pn * 2 * hstepB;
; #pragma unroll 1
;         for (int t = 0; t < nt; t += 2) {
;             const bool last = (t == nt - 2);
;             const char* a1 = AS.tile(cur, t + 1);
;             const char* a2 = last ? AS.tile(nu, 0) : AS.tile(cur, t + 2); const char* b2 = last ? nB : cB + (size_t)(t + 2) * kstep;
;             const char* a3 = last ? AS.tile(nu, 1) : AS.tile(cur, t + 3); const char* b3 = b2 + kstep;
;             PG8_LDB(B0, 0, 0); PG8_LDB(B1, 0, 1); PG8_SCHED; PG8_LDA(At, 0, 0); PG8_STAGE(PG8_SA(1, 1), a1 + hstepA, voffA);
;             PG8_WAIT_V(8); PG8_WAIT_L(0); PG8_BAR; PG8_MMA(0, 0, At, B0); PG8_MMA(0, 1, At, B1); PG8_BAR; PG8_SCHED;
;             PG8_LDA(At, 0, 1); PG8_STAGE(PG8_SB(0, 0), b2, voffB); PG8_STAGE(PG8_SB(0, 1), b2 + hstepB, voffB); PG8_STAGE(PG8_SA(0, 0), a2, voffA);
;             PG8_WAIT_V(8); PG8_WAIT_L(0); PG8_BAR; PG8_MMA(1, 0, At, B0); PG8_MMA(1, 1, At, B1); PG8_BAR; PG8_SCHED;
.LBB0_379:
	s_and_b64 s[2:3], exec, s[44:45]
	s_cselect_b32 s3, s26, s73
	s_cselect_b32 s2, s0, s74
	s_ashr_i64 s[24:25], s[2:3], 13
	s_and_b32 s24, s24, 0xfff80000
	s_add_u32 s75, s53, s24
	s_addc_u32 s76, s54, s25
	s_ashr_i32 s1, s0, 31
	s_lshl_b64 s[46:47], s[0:1], 19
	s_add_u32 s1, s55, s46
	s_mov_b32 s48, s97
	s_mov_b32 s49, s2
	s_addc_u32 s77, s56, s47
	s_ashr_i64 s[2:3], s[48:49], 13
	s_add_u32 s78, s55, s2
	s_addc_u32 s79, s56, s3
	s_add_u32 s80, s78, 0x80
	s_addc_u32 s81, s79, 0
	s_add_u32 s82, s69, s28
	v_lshl_add_u64 v[128:129], v[154:155], 0, s[46:47]
	v_lshl_add_u64 v[130:131], v[156:157], 0, s[46:47]
	s_addc_u32 s83, s70, s29
	s_mov_b32 s84, -2
	s_mov_b64 s[2:3], 0
	s_mov_b64 s[90:91], 0x80
.Lpeel_380:
	s_add_u32 s28, s1, s2
	s_addc_u32 s29, s77, s3
	s_add_u32 s48, s28, 0x100
	s_addc_u32 s49, s29, 0
	s_add_u32 s46, s82, s2
	s_addc_u32 s47, s83, s3
	s_add_u32 s28, s28, 0x180
	s_addc_u32 s29, s29, 0
	s_add_i32 s85, 0, 0x10000
	s_add_i32 s88, 0, 0x14000
	v_add_u32_e32 v158, s85, v174
	v_add_u32_e32 v186, s88, v174
	ds_read_b128 v[132:135], v158
	ds_read_b128 v[136:139], v158 offset:1024
	ds_read_b128 v[140:143], v158 offset:2048
	ds_read_b128 v[158:161], v158 offset:3072
	ds_read_b128 v[162:165], v186
	ds_read_b128 v[166:169], v186 offset:1024
	ds_read_b128 v[182:185], v186 offset:2048
	ds_read_b128 v[186:189], v186 offset:3072
	s_cmpk_eq_i32 s2, 0x700
	s_cselect_b32 s29, s81, s29
	s_cselect_b32 s28, s80, s28
	s_cselect_b32 s47, s76, s47
	s_cselect_b32 s46, s75, s46
	s_cselect_b32 s49, s79, s49
	s_cselect_b32 s48, s78, s48
	v_lshl_add_u64 v[222:223], v[128:129], 0, s[2:3]
	s_add_i32 m0, s27, 0xc000
	ds_read_b128 v[190:193], v180
	ds_read_b128 v[194:197], v180 offset:1024
	ds_read_b128 v[198:201], v180 offset:2048
	ds_read_b128 v[204:207], v180 offset:3072
	ds_read_b128 v[218:221], v180 offset:4096
	ds_read_b128 v[238:241], v180 offset:5120
	ds_read_b128 v[242:245], v180 offset:6144
	ds_read_b128 v[246:249], v180 offset:7168
	global_load_lds_dwordx4 v[222:223], off
	v_lshl_add_u64 v[222:223], v[130:131], 0, s[2:3]
	s_add_i32 m0, s27, 0xe000
	s_nop 0
	global_load_lds_dwordx4 v[222:223], off
	s_waitcnt vmcnt(8)
	s_waitcnt lgkmcnt(0)
	s_barrier
	s_setprio 1
	s_waitcnt lgkmcnt(0)
	v_mfma_f32_16x16x32_bf16 v[124:127], v[132:135], v[190:193], 0
	v_mfma_f32_16x16x32_bf16 v[120:123], v[140:143], v[190:193], 0
	v_mfma_f32_16x16x32_bf16 v[108:111], v[132:135], v[198:201], 0
	v_mfma_f32_16x16x32_bf16 v[104:107], v[140:143], v[198:201], 0
	v_mfma_f32_16x16x32_bf16 v[92:95], v[132:135], v[218:221], 0
	v_mfma_f32_16x16x32_bf16 v[88:91], v[140:143], v[218:221], 0
	v_mfma_f32_16x16x32_bf16 v[76:79], v[132:135], v[242:245], 0
	v_mfma_f32_16x16x32_bf16 v[72:75], v[140:143], v[242:245], 0
	v_mfma_f32_16x16x32_bf16 v[124:127], v[136:139], v[194:197], v[124:127]
	v_mfma_f32_16x16x32_bf16 v[120:123], v[158:161], v[194:197], v[120:123]
	v_mfma_f32_16x16x32_bf16 v[108:111], v[136:139], v[204:207], v[108:111]
	v_mfma_f32_16x16x32_bf16 v[104:107], v[158:161], v[204:207], v[104:107]
	v_mfma_f32_16x16x32_bf16 v[92:95], v[136:139], v[238:241], v[92:95]
	v_mfma_f32_16x16x32_bf16 v[88:91], v[158:161], v[238:241], v[88:91]
	v_mfma_f32_16x16x32_bf16 v[76:79], v[136:139], v[246:249], v[76:79]
	v_mfma_f32_16x16x32_bf16 v[72:75], v[158:161], v[246:249], v[72:75]
	s_setprio 0
	s_setprio 1
	v_mfma_f32_16x16x32_bf16 v[116:119], v[162:165], v[190:193], 0
	v_mfma_f32_16x16x32_bf16 v[112:115], v[182:185], v[190:193], 0
	v_mfma_f32_16x16x32_bf16 v[100:103], v[162:165], v[198:201], 0
	v_mfma_f32_16x16x32_bf16 v[96:99], v[182:185], v[198:201], 0
	v_mfma_f32_16x16x32_bf16 v[84:87], v[162:165], v[218:221], 0
	v_mfma_f32_16x16x32_bf16 v[80:83], v[182:185], v[218:221], 0
	v_mfma_f32_16x16x32_bf16 v[68:71], v[162:165], v[242:245], 0
	v_mfma_f32_16x16x32_bf16 v[64:67], v[182:185], v[242:245], 0
	v_mfma_f32_16x16x32_bf16 v[116:119], v[166:169], v[194:197], v[116:119]
	v_mfma_f32_16x16x32_bf16 v[112:115], v[186:189], v[194:197], v[112:115]
	v_mfma_f32_16x16x32_bf16 v[100:103], v[166:169], v[204:207], v[100:103]
	v_mfma_f32_16x16x32_bf16 v[96:99], v[186:189], v[204:207], v[96:99]
	v_mfma_f32_16x16x32_bf16 v[84:87], v[166:169], v[238:241], v[84:87]
	v_mfma_f32_16x16x32_bf16 v[80:83], v[186:189], v[238:241], v[80:83]
	v_mfma_f32_16x16x32_bf16 v[68:71], v[166:169], v[246:249], v[68:71]
	v_mfma_f32_16x16x32_bf16 v[64:67], v[186:189], v[246:249], v[64:67]
	s_setprio 0
	s_barrier
	s_add_i32 s85, s85, s52
	v_lshl_add_u64 v[222:223], s[46:47], 0, v[146:147]
	s_mov_b32 m0, s85
	ds_read_b128 v[190:193], v180 offset:16384
	ds_read_b128 v[194:197], v180 offset:17408
	ds_read_b128 v[198:201], v180 offset:18432
	ds_read_b128 v[204:207], v180 offset:19456
	ds_read_b128 v[218:221], v180 offset:20480
	ds_read_b128 v[238:241], v180 offset:21504
	ds_read_b128 v[242:245], v180 offset:22528
	ds_read_b128 v[246:249], v180 offset:23552
	global_load_lds_dwordx4 v[222:223], off
	s_add_i32 m0, s85, 0x2000
	s_add_u32 s86, s46, 0x40000
	v_lshl_add_u64 v[224:225], s[46:47], 0, v[150:151]
	s_addc_u32 s87, s47, 0
	s_add_i32 s85, s88, s52
	global_load_lds_dwordx4 v[224:225], off
	v_lshl_add_u64 v[250:251], s[86:87], 0, v[146:147]
	s_mov_b32 m0, s85
	s_nop 0
	global_load_lds_dwordx4 v[250:251], off
	v_lshl_add_u64 v[250:251], s[86:87], 0, v[150:151]
	s_add_i32 m0, s85, 0x2000
	s_nop 0
	global_load_lds_dwordx4 v[250:251], off
	v_lshl_add_u64 v[250:251], s[48:49], 0, v[144:145]
	s_mov_b32 m0, s27
	s_nop 0
	global_load_lds_dwordx4 v[250:251], off
	v_lshl_add_u64 v[250:251], s[48:49], 0, v[148:149]
	s_mov_b32 m0, s57
	s_nop 0
	global_load_lds_dwordx4 v[250:251], off
	s_waitcnt vmcnt(8)
	s_waitcnt lgkmcnt(0)
	s_barrier
; #define PG8_STAGE(bufoff, gbase, voff) do { _Pragma("unroll") for (int _i = 0; _i < 2; ++_i) \
;         __builtin_amdgcn_global_load_lds((const unsigned*)((const char*)(gbase) + (voff)[_i]), (PG8_LAS unsigned*)(lds + (bufoff) + ldsw + _i * 8192), 16, 0, 0); } while (0)
; #define PG8_LDA(dst, b, h) do { _Pragma("unroll") for (int m = 0; m < 4; ++m) _Pragma("unroll") for (int k = 0; k < 2; ++k) dst[m][k] = *(const PG8_LAS bf16x8*)(lds + PG8_SA(b, h) + aoff + m * 2048 + k * 1024); } while (0)
; #define PG8_LDB(dst, b, h) do { _Pragma("unroll") for (int n = 0; n < 2; ++n) _Pragma("unroll") for (int k = 0; k < 2; ++k) dst[n][k] = *(const PG8_LAS bf16x8*)(lds + PG8_SB(b, h) + boff + n * 2048 + k * 1024); } while (0)
; #define PG8_MMA(ai, bj, At, Bt) do { __builtin_amdgcn_s_setprio(1); _Pragma("unroll") for (int m = 0; m < 4; ++m) _Pragma("unroll") for (int n = 0; n < 2; ++n) _Pragma("unroll") for (int k = 0; k < 2; ++k) \
;         acc[ai][bj][m][n] = __builtin_amdgcn_mfma_f32_16x16x32_bf16(Bt[n][k], At[m][k], acc[ai][bj][m][n], 0, 0, 0); __builtin_amdgcn_s_setprio(0); } while (0)
; #define PG8_WAIT_V(n) asm volatile("s_waitcnt vmcnt(" #n ")" ::: "memory")
; #define PG8_WAIT_L(n) asm volatile("s_waitcnt lgkmcnt(" #n ")" ::: "memory")
; #define PG8_BAR __builtin_amdgcn_s_barrier()
; #define PG8_SCHED __builtin_amdgcn_sched_barrier(0)
;     ...
;             PG8_WAIT_V(8); PG8_WAIT_L(0); PG8_BAR; PG8_MMA(1, 0, At, B0); PG8_MMA(1, 1, At, B1); PG8_BAR; PG8_SCHED;
;             PG8_LDB(B0, 1, 0); PG8_LDB(B1, 1, 1); PG8_SCHED; PG8_LDA(At, 1, 0); PG8_STAGE(PG8_SA(0, 1), a2 + hstepA, voffA);
;             PG8_WAIT_V(8); PG8_WAIT_L(0); PG8_BAR; PG8_MMA(0, 0, At, B0); PG8_MMA(0, 1, At, B1); PG8_BAR; PG8_SCHED;
	s_setprio 1
	s_waitcnt lgkmcnt(0)
	v_mfma_f32_16x16x32_bf16 v[60:63], v[132:135], v[190:193], 0
	v_mfma_f32_16x16x32_bf16 v[56:59], v[140:143], v[190:193], 0
	v_mfma_f32_16x16x32_bf16 v[44:47], v[132:135], v[198:201], 0
	v_mfma_f32_16x16x32_bf16 v[40:43], v[140:143], v[198:201], 0
	v_mfma_f32_16x16x32_bf16 v[28:31], v[132:135], v[218:221], 0
	v_mfma_f32_16x16x32_bf16 v[24:27], v[140:143], v[218:221], 0
	v_mfma_f32_16x16x32_bf16 v[12:15], v[132:135], v[242:245], 0
	v_mfma_f32_16x16x32_bf16 v[8:11], v[140:143], v[242:245], 0
	v_mfma_f32_16x16x32_bf16 v[60:63], v[136:139], v[194:197], v[60:63]
	v_mfma_f32_16x16x32_bf16 v[56:59], v[158:161], v[194:197], v[56:59]
	v_mfma_f32_16x16x32_bf16 v[44:47], v[136:139], v[204:207], v[44:47]
	v_mfma_f32_16x16x32_bf16 v[40:43], v[158:161], v[204:207], v[40:43]
	v_mfma_f32_16x16x32_bf16 v[28:31], v[136:139], v[238:241], v[28:31]
	v_mfma_f32_16x16x32_bf16 v[24:27], v[158:161], v[238:241], v[24:27]
	v_mfma_f32_16x16x32_bf16 v[12:15], v[136:139], v[246:249], v[12:15]
	v_mfma_f32_16x16x32_bf16 v[8:11], v[158:161], v[246:249], v[8:11]
	s_setprio 0
	s_setprio 1
	v_mfma_f32_16x16x32_bf16 v[52:55], v[162:165], v[190:193], 0
	v_mfma_f32_16x16x32_bf16 v[48:51], v[182:185], v[190:193], 0
	v_mfma_f32_16x16x32_bf16 v[36:39], v[162:165], v[198:201], 0
	v_mfma_f32_16x16x32_bf16 v[32:35], v[182:185], v[198:201], 0
	v_mfma_f32_16x16x32_bf16 v[20:23], v[162:165], v[218:221], 0
	v_mfma_f32_16x16x32_bf16 v[16:19], v[182:185], v[218:221], 0
	v_mfma_f32_16x16x32_bf16 v[4:7], v[162:165], v[242:245], 0
	v_mfma_f32_16x16x32_bf16 v[0:3], v[182:185], v[242:245], 0
	v_mfma_f32_16x16x32_bf16 v[52:55], v[166:169], v[194:197], v[52:55]
	v_mfma_f32_16x16x32_bf16 v[48:51], v[186:189], v[194:197], v[48:51]
	v_mfma_f32_16x16x32_bf16 v[36:39], v[166:169], v[204:207], v[36:39]
	v_mfma_f32_16x16x32_bf16 v[32:35], v[186:189], v[204:207], v[32:35]
	v_mfma_f32_16x16x32_bf16 v[20:23], v[166:169], v[238:241], v[20:23]
	v_mfma_f32_16x16x32_bf16 v[16:19], v[186:189], v[238:241], v[16:19]
	v_mfma_f32_16x16x32_bf16 v[4:7], v[166:169], v[246:249], v[4:7]
	v_mfma_f32_16x16x32_bf16 v[0:3], v[186:189], v[246:249], v[0:3]
	s_setprio 0
	s_barrier
	s_add_i32 s85, 0, 0x18000
	s_add_i32 s86, 0, 0x1c000
	v_add_u32_e32 v158, s85, v174
	v_add_u32_e32 v186, s86, v174
	ds_read_b128 v[132:135], v158
	ds_read_b128 v[136:139], v158 offset:1024
	ds_read_b128 v[140:143], v158 offset:2048
	ds_read_b128 v[158:161], v158 offset:3072
	ds_read_b128 v[162:165], v186
	ds_read_b128 v[166:169], v186 offset:1024
	ds_read_b128 v[182:185], v186 offset:2048
	ds_read_b128 v[186:189], v186 offset:3072
	s_add_u32 s48, s48, 0x40000
	s_addc_u32 s49, s49, 0
	s_mov_b32 m0, s58
	v_lshl_add_u64 v[250:251], s[48:49], 0, v[144:145]
	ds_read_b128 v[190:193], v180 offset:32768
	ds_read_b128 v[194:197], v180 offset:33792
	ds_read_b128 v[198:201], v180 offset:34816
	ds_read_b128 v[204:207], v180 offset:35840
	ds_read_b128 v[218:221], v180 offset:36864
	ds_read_b128 v[238:241], v180 offset:37888
	ds_read_b128 v[242:245], v180 offset:38912
	ds_read_b128 v[246:249], v180 offset:39936
	global_load_lds_dwordx4 v[250:251], off
	v_lshl_add_u64 v[250:251], s[48:49], 0, v[148:149]
	s_mov_b32 m0, s59
	s_nop 0
	global_load_lds_dwordx4 v[250:251], off
	s_waitcnt vmcnt(8)
	s_waitcnt lgkmcnt(0)
	s_barrier
	s_setprio 1
	s_waitcnt lgkmcnt(0)
	v_mfma_f32_16x16x32_bf16 v[124:127], v[132:135], v[190:193], v[124:127]
	v_mfma_f32_16x16x32_bf16 v[120:123], v[140:143], v[190:193], v[120:123]
	v_mfma_f32_16x16x32_bf16 v[108:111], v[132:135], v[198:201], v[108:111]
	v_mfma_f32_16x16x32_bf16 v[104:107], v[140:143], v[198:201], v[104:107]
	v_mfma_f32_16x16x32_bf16 v[92:95], v[132:135], v[218:221], v[92:95]
	v_mfma_f32_16x16x32_bf16 v[88:91], v[140:143], v[218:221], v[88:91]
	v_mfma_f32_16x16x32_bf16 v[76:79], v[132:135], v[242:245], v[76:79]
	v_mfma_f32_16x16x32_bf16 v[72:75], v[140:143], v[242:245], v[72:75]
	v_mfma_f32_16x16x32_bf16 v[124:127], v[136:139], v[194:197], v[124:127]
	v_mfma_f32_16x16x32_bf16 v[120:123], v[158:161], v[194:197], v[120:123]
	v_mfma_f32_16x16x32_bf16 v[108:111], v[136:139], v[204:207], v[108:111]
	v_mfma_f32_16x16x32_bf16 v[104:107], v[158:161], v[204:207], v[104:107]
	v_mfma_f32_16x16x32_bf16 v[92:95], v[136:139], v[238:241], v[92:95]
	v_mfma_f32_16x16x32_bf16 v[88:91], v[158:161], v[238:241], v[88:91]
	v_mfma_f32_16x16x32_bf16 v[76:79], v[136:139], v[246:249], v[76:79]
	v_mfma_f32_16x16x32_bf16 v[72:75], v[158:161], v[246:249], v[72:75]
	s_setprio 0
	s_setprio 1
	v_mfma_f32_16x16x32_bf16 v[116:119], v[162:165], v[190:193], v[116:119]
	v_mfma_f32_16x16x32_bf16 v[112:115], v[182:185], v[190:193], v[112:115]
	v_mfma_f32_16x16x32_bf16 v[100:103], v[162:165], v[198:201], v[100:103]
	v_mfma_f32_16x16x32_bf16 v[96:99], v[182:185], v[198:201], v[96:99]
	v_mfma_f32_16x16x32_bf16 v[84:87], v[162:165], v[218:221], v[84:87]
	v_mfma_f32_16x16x32_bf16 v[80:83], v[182:185], v[218:221], v[80:83]
	v_mfma_f32_16x16x32_bf16 v[68:71], v[162:165], v[242:245], v[68:71]
	v_mfma_f32_16x16x32_bf16 v[64:67], v[182:185], v[242:245], v[64:67]
	v_mfma_f32_16x16x32_bf16 v[116:119], v[166:169], v[194:197], v[116:119]
	v_mfma_f32_16x16x32_bf16 v[112:115], v[186:189], v[194:197], v[112:115]
	v_mfma_f32_16x16x32_bf16 v[100:103], v[166:169], v[204:207], v[100:103]
	v_mfma_f32_16x16x32_bf16 v[96:99], v[186:189], v[204:207], v[96:99]
	v_mfma_f32_16x16x32_bf16 v[84:87], v[166:169], v[238:241], v[84:87]
	v_mfma_f32_16x16x32_bf16 v[80:83], v[186:189], v[238:241], v[80:83]
	v_mfma_f32_16x16x32_bf16 v[68:71], v[166:169], v[246:249], v[68:71]
	v_mfma_f32_16x16x32_bf16 v[64:67], v[186:189], v[246:249], v[64:67]
	s_setprio 0
	s_barrier
; #define PG8_STAGE(bufoff, gbase, voff) do { _Pragma("unroll") for (int _i = 0; _i < 2; ++_i) \
;         __builtin_amdgcn_global_load_lds((const unsigned*)((const char*)(gbase) + (voff)[_i]), (PG8_LAS unsigned*)(lds + (bufoff) + ldsw + _i * 8192), 16, 0, 0); } while (0)
; #define PG8_LDA(dst, b, h) do { _Pragma("unroll") for (int m = 0; m < 4; ++m) _Pragma("unroll") for (int k = 0; k < 2; ++k) dst[m][k] = *(const PG8_LAS bf16x8*)(lds + PG8_SA(b, h) + aoff + m * 2048 + k * 1024); } while (0)
; #define PG8_MMA(ai, bj, At, Bt) do { __builtin_amdgcn_s_setprio(1); _Pragma("unroll") for (int m = 0; m < 4; ++m) _Pragma("unroll") for (int n = 0; n < 2; ++n) _Pragma("unroll") for (int k = 0; k < 2; ++k) \
;         acc[ai][bj][m][n] = __builtin_amdgcn_mfma_f32_16x16x32_bf16(Bt[n][k], At[m][k], acc[ai][bj][m][n], 0, 0, 0); __builtin_amdgcn_s_setprio(0); } while (0)
; #define PG8_WAIT_V(n) asm volatile("s_waitcnt vmcnt(" #n ")" ::: "memory")
; #define PG8_WAIT_L(n) asm volatile("s_waitcnt lgkmcnt(" #n ")" ::: "memory")
; #define PG8_BAR __builtin_amdgcn_s_barrier()
; #define PG8_SCHED __builtin_amdgcn_sched_barrier(0)
;     ...
;         for (int t = 0; t < nt; t += 2) {
;             const bool last = (t == nt - 2);
;     ...
;             PG8_LDA(At, 1, 1); PG8_STAGE(PG8_SB(1, 0), b3, voffB); PG8_STAGE(PG8_SB(1, 1), b3 + hstepB, voffB); PG8_STAGE(PG8_SA(1, 0), a3, voffA);
;             PG8_WAIT_V(8); PG8_WAIT_L(0); PG8_BAR; PG8_MMA(1, 0, At, B0); PG8_MMA(1, 1, At, B1); PG8_BAR; PG8_SCHED;
	s_add_i32 s48, s85, s52
	v_lshl_add_u64 v[222:223], v[222:223], 0, s[90:91]
	s_mov_b32 m0, s48
	ds_read_b128 v[190:193], v180 offset:49152
	ds_read_b128 v[194:197], v180 offset:50176
	ds_read_b128 v[198:201], v180 offset:51200
	ds_read_b128 v[204:207], v180 offset:52224
	ds_read_b128 v[218:221], v180 offset:53248
	ds_read_b128 v[238:241], v180 offset:54272
	ds_read_b128 v[242:245], v180 offset:55296
	ds_read_b128 v[246:249], v180 offset:56320
	global_load_lds_dwordx4 v[222:223], off
	s_add_i32 m0, s48, 0x2000
	s_add_u32 s46, s46, 0x40080
	v_lshl_add_u64 v[222:223], v[224:225], 0, s[90:91]
	s_addc_u32 s47, s47, 0
	s_add_i32 s48, s86, s52
	global_load_lds_dwordx4 v[222:223], off
	v_lshl_add_u64 v[222:223], s[46:47], 0, v[146:147]
	s_mov_b32 m0, s48
	s_nop 0
	global_load_lds_dwordx4 v[222:223], off
	v_lshl_add_u64 v[222:223], s[46:47], 0, v[150:151]
	s_add_i32 m0, s48, 0x2000
	s_nop 0
	global_load_lds_dwordx4 v[222:223], off
	v_lshl_add_u64 v[222:223], s[28:29], 0, v[144:145]
	s_mov_b32 m0, s60
	s_nop 0
	global_load_lds_dwordx4 v[222:223], off
	v_lshl_add_u64 v[222:223], s[28:29], 0, v[148:149]
	s_mov_b32 m0, s61
	s_nop 0
	global_load_lds_dwordx4 v[222:223], off
	s_waitcnt vmcnt(8)
	s_waitcnt lgkmcnt(0)
	s_barrier
	s_setprio 1
	s_waitcnt lgkmcnt(0)
	v_mfma_f32_16x16x32_bf16 v[60:63], v[132:135], v[190:193], v[60:63]
	v_mfma_f32_16x16x32_bf16 v[56:59], v[140:143], v[190:193], v[56:59]
	v_mfma_f32_16x16x32_bf16 v[44:47], v[132:135], v[198:201], v[44:47]
	v_mfma_f32_16x16x32_bf16 v[40:43], v[140:143], v[198:201], v[40:43]
	v_mfma_f32_16x16x32_bf16 v[28:31], v[132:135], v[218:221], v[28:31]
	v_mfma_f32_16x16x32_bf16 v[24:27], v[140:143], v[218:221], v[24:27]
	v_mfma_f32_16x16x32_bf16 v[12:15], v[132:135], v[242:245], v[12:15]
	v_mfma_f32_16x16x32_bf16 v[8:11], v[140:143], v[242:245], v[8:11]
	v_mfma_f32_16x16x32_bf16 v[60:63], v[136:139], v[194:197], v[60:63]
	v_mfma_f32_16x16x32_bf16 v[56:59], v[158:161], v[194:197], v[56:59]
	v_mfma_f32_16x16x32_bf16 v[44:47], v[136:139], v[204:207], v[44:47]
	v_mfma_f32_16x16x32_bf16 v[40:43], v[158:161], v[204:207], v[40:43]
	v_mfma_f32_16x16x32_bf16 v[28:31], v[136:139], v[238:241], v[28:31]
	v_mfma_f32_16x16x32_bf16 v[24:27], v[158:161], v[238:241], v[24:27]
	v_mfma_f32_16x16x32_bf16 v[12:15], v[136:139], v[246:249], v[12:15]
	v_mfma_f32_16x16x32_bf16 v[8:11], v[158:161], v[246:249], v[8:11]
	s_setprio 0
	s_setprio 1
	v_mfma_f32_16x16x32_bf16 v[52:55], v[162:165], v[190:193], v[52:55]
	v_mfma_f32_16x16x32_bf16 v[48:51], v[182:185], v[190:193], v[48:51]
	v_mfma_f32_16x16x32_bf16 v[36:39], v[162:165], v[198:201], v[36:39]
	v_mfma_f32_16x16x32_bf16 v[32:35], v[182:185], v[198:201], v[32:35]
	v_mfma_f32_16x16x32_bf16 v[20:23], v[162:165], v[218:221], v[20:23]
	v_mfma_f32_16x16x32_bf16 v[16:19], v[182:185], v[218:221], v[16:19]
	v_mfma_f32_16x16x32_bf16 v[4:7], v[162:165], v[242:245], v[4:7]
	v_mfma_f32_16x16x32_bf16 v[0:3], v[182:185], v[242:245], v[0:3]
	v_mfma_f32_16x16x32_bf16 v[52:55], v[166:169], v[194:197], v[52:55]
	v_mfma_f32_16x16x32_bf16 v[48:51], v[186:189], v[194:197], v[48:51]
	v_mfma_f32_16x16x32_bf16 v[36:39], v[166:169], v[204:207], v[36:39]
	v_mfma_f32_16x16x32_bf16 v[32:35], v[186:189], v[204:207], v[32:35]
	v_mfma_f32_16x16x32_bf16 v[20:23], v[166:169], v[238:241], v[20:23]
	v_mfma_f32_16x16x32_bf16 v[16:19], v[186:189], v[238:241], v[16:19]
	v_mfma_f32_16x16x32_bf16 v[4:7], v[166:169], v[246:249], v[4:7]
	v_mfma_f32_16x16x32_bf16 v[0:3], v[186:189], v[246:249], v[0:3]
	s_setprio 0
	s_barrier
	s_add_i32 s84, s84, 2
	s_add_u32 s2, s2, 0x100
	s_addc_u32 s3, s3, 0
	s_cmp_gt_u32 s84, 13
	s_cbranch_scc0 .LBB0_380
	s_branch .Lpeel_exit_380

; #define PG8_BAR __builtin_amdgcn_s_barrier()
;     ...
;         if (wr == 0) PG8_BAR;
;         if (!has_next && wmat && gtid * 128u < wbytes) asm volatile("global_load_dword %0, %1, off" : "+v"(warmm) : "v"(wmat + (size_t)gtid * 128u) : "memory");
.Lpeel_exit_380:
	s_and_b64 vcc, exec, s[30:31]
	s_cbranch_vccz .LBB0_385
	s_barrier
	s_and_b64 s[28:29], s[20:21], s[44:45]
	s_and_saveexec_b64 s[2:3], s[28:29]
	s_cbranch_execnz .LBB0_386

;     __device__ __forceinline__ const char* tile(const Unit& u, int t) const { return A + (size_t)u.pm * 2 * hstep() + (size_t)t * (BK * 2); }
;     __device__ __forceinline__ const char* tile(const Unit& u, int t) const { return U + (long)(t >> 2) * xoff + (size_t)u.pn * (1024 * 512) + (size_t)u.pm * 2 * hstep() + (size_t)(t & 3) * (BK * 2); }
; #define PG8_STAGE(bufoff, gbase, voff) do { _Pragma("unroll") for (int _i = 0; _i < 2; ++_i) \
;         __builtin_amdgcn_global_load_lds((const unsigned*)((const char*)(gbase) + (voff)[_i]), (PG8_LAS unsigned*)(lds + (bufoff) + ldsw + _i * 8192), 16, 0, 0); } while (0)
; #define PG8_LDA(dst, b, h) do { _Pragma("unroll") for (int m = 0; m < 4; ++m) _Pragma("unroll") for (int k = 0; k < 2; ++k) dst[m][k] = *(const PG8_LAS bf16x8*)(lds + PG8_SA(b, h) + aoff + m * 2048 + k * 1024); } while (0)
; #define PG8_LDB(dst, b, h) do { _Pragma("unroll") for (int n = 0; n < 2; ++n) _Pragma("unroll") for (int k = 0; k < 2; ++k) dst[n][k] = *(const PG8_LAS bf16x8*)(lds + PG8_SB(b, h) + boff + n * 2048 + k * 1024); } while (0)
; #define PG8_WAIT_V(n) asm volatile("s_waitcnt vmcnt(" #n ")" ::: "memory")
; #define PG8_WAIT_L(n) asm volatile("s_waitcnt lgkmcnt(" #n ")" ::: "memory")
; #define PG8_BAR __builtin_amdgcn_s_barrier()
; #define PG8_SCHED __builtin_amdgcn_sched_barrier(0)
;     ...
;         const bool has_next = S.next(ui + 1, nxt);
;         const Unit nu = has_next ? nxt : cur;
;         const char* nB = (const char*)g.Bt + (size_t)nu.pn * 2 * hstepB;
; #pragma unroll 1
;         for (int t = 0; t < nt; t += 2) {
;             const bool last = (t == nt - 2);
;             const char* a1 = AS.tile(cur, t + 1);
;             const char* a2 = last ? AS.tile(nu, 0) : AS.tile(cur, t + 2); const char* b2 = last ? nB : cB + (size_t)(t + 2) * kstep;
;             const char* a3 = last ? AS.tile(nu, 1) : AS.tile(cur, t + 3); const char* b3 = b2 + kstep;
;             PG8_LDB(B0, 0, 0); PG8_LDB(B1, 0, 1); PG8_SCHED; PG8_LDA(At, 0, 0); PG8_STAGE(PG8_SA(1, 1), a1 + hstepA, voffA);
;             PG8_WAIT_V(8); PG8_WAIT_L(0); PG8_BAR; PG8_MMA(0, 0, At, B0); PG8_MMA(0, 1, At, B1); PG8_BAR; PG8_SCHED;
;             PG8_LDA(At, 0, 1); PG8_STAGE(PG8_SB(0, 0), b2, voffB); PG8_STAGE(PG8_SB(0, 1), b2 + hstepB, voffB); PG8_STAGE(PG8_SA(0, 0), a2, voffA);
.LBB0_450:
	s_and_b64 s[0:1], s[40:41], exec
	s_cselect_b32 s21, s53, s55
	s_cselect_b32 s20, s54, s2
	s_ashr_i64 s[0:1], s[20:21], 13
	s_and_b32 s0, s0, 0xfff80000
	s_add_u32 s56, s5, s0
	s_addc_u32 s57, s28, s1
	s_ashr_i32 s3, s2, 31
	s_mov_b32 s26, s97
	s_mov_b32 s27, s20
	s_lshl_b64 s[24:25], s[2:3], 19
	s_ashr_i64 s[20:21], s[26:27], 13
	s_add_u32 s3, s29, s20
	s_addc_u32 s58, s30, s21
	s_add_u32 s59, s3, 0x80
	s_addc_u32 s60, s58, 0
	v_readlane_b32 s20, v254, 33
	v_readlane_b32 s21, v254, 34
	s_add_u32 s61, s20, s24
	s_addc_u32 s64, s21, s25
	s_add_u32 s65, s50, s18
	s_mov_b64 s[72:73], 0x80
	v_lshl_add_u64 v[112:113], v[166:167], 0, s[24:25]
	v_lshl_add_u64 v[114:115], v[168:169], 0, s[24:25]
	s_addc_u32 s66, s51, s19
	s_mov_b32 s67, -2
	s_mov_b64 s[18:19], 0
.Lpeel_451:
	s_add_u32 s20, s61, s18
	s_addc_u32 s21, s64, s19
	s_add_u32 s26, s20, 0x3600100
	s_addc_u32 s27, s21, 0
	s_add_u32 s24, s65, s18
	s_addc_u32 s25, s66, s19
	s_add_u32 s20, s20, 0x3600180
	s_addc_u32 s21, s21, 0
	s_add_i32 s68, 0, 0x10000
	s_add_i32 s70, 0, 0x14000
	v_add_u32_e32 v144, s68, v203
	v_add_u32_e32 v174, s70, v203
	ds_read_b128 v[132:135], v144
	ds_read_b128 v[136:139], v144 offset:1024
	ds_read_b128 v[140:143], v144 offset:2048
	ds_read_b128 v[144:147], v144 offset:3072
	ds_read_b128 v[148:151], v174
	ds_read_b128 v[152:155], v174 offset:1024
	ds_read_b128 v[170:173], v174 offset:2048
	ds_read_b128 v[174:177], v174 offset:3072
	s_cmpk_eq_i32 s18, 0x700
	s_cselect_b32 s21, s60, s21
	s_cselect_b32 s20, s59, s20
	s_cselect_b32 s25, s57, s25
	s_cselect_b32 s24, s56, s24
	s_cselect_b32 s27, s58, s27
	s_cselect_b32 s26, s3, s26
	v_lshl_add_u64 v[238:239], v[112:113], 0, s[18:19]
	s_add_i32 m0, s35, 0xc000
	ds_read_b128 v[178:181], v211
	ds_read_b128 v[182:185], v211 offset:1024
	ds_read_b128 v[186:189], v211 offset:2048
	ds_read_b128 v[190:193], v211 offset:3072
	ds_read_b128 v[194:197], v211 offset:4096
	ds_read_b128 v[198:201], v211 offset:5120
	ds_read_b128 v[218:221], v211 offset:6144
	ds_read_b128 v[222:225], v211 offset:7168
	global_load_lds_dwordx4 v[238:239], off
	v_lshl_add_u64 v[238:239], v[114:115], 0, s[18:19]
	s_add_i32 m0, s35, 0xe000
	s_nop 0
	global_load_lds_dwordx4 v[238:239], off
	s_waitcnt vmcnt(8)
	s_waitcnt lgkmcnt(0)
	s_barrier
	s_setprio 1
	s_waitcnt lgkmcnt(0)
	v_mfma_f32_16x16x32_bf16 v[120:123], v[132:135], v[178:181], 0
	v_mfma_f32_16x16x32_bf16 v[116:119], v[140:143], v[178:181], 0
	v_mfma_f32_16x16x32_bf16 v[108:111], v[132:135], v[186:189], 0
	v_mfma_f32_16x16x32_bf16 v[104:107], v[140:143], v[186:189], 0
	v_mfma_f32_16x16x32_bf16 v[92:95], v[132:135], v[194:197], 0
	v_mfma_f32_16x16x32_bf16 v[88:91], v[140:143], v[194:197], 0
	v_mfma_f32_16x16x32_bf16 v[76:79], v[132:135], v[218:221], 0
	v_mfma_f32_16x16x32_bf16 v[72:75], v[140:143], v[218:221], 0
	v_mfma_f32_16x16x32_bf16 v[120:123], v[136:139], v[182:185], v[120:123]
	v_mfma_f32_16x16x32_bf16 v[116:119], v[144:147], v[182:185], v[116:119]
	v_mfma_f32_16x16x32_bf16 v[108:111], v[136:139], v[190:193], v[108:111]
	v_mfma_f32_16x16x32_bf16 v[104:107], v[144:147], v[190:193], v[104:107]
	v_mfma_f32_16x16x32_bf16 v[92:95], v[136:139], v[198:201], v[92:95]
	v_mfma_f32_16x16x32_bf16 v[88:91], v[144:147], v[198:201], v[88:91]
	v_mfma_f32_16x16x32_bf16 v[76:79], v[136:139], v[222:225], v[76:79]
	v_mfma_f32_16x16x32_bf16 v[72:75], v[144:147], v[222:225], v[72:75]
	s_setprio 0
	s_setprio 1
	v_mfma_f32_16x16x32_bf16 v[128:131], v[148:151], v[178:181], 0
	v_mfma_f32_16x16x32_bf16 v[124:127], v[170:173], v[178:181], 0
	v_mfma_f32_16x16x32_bf16 v[100:103], v[148:151], v[186:189], 0
	v_mfma_f32_16x16x32_bf16 v[96:99], v[170:173], v[186:189], 0
	v_mfma_f32_16x16x32_bf16 v[84:87], v[148:151], v[194:197], 0
	v_mfma_f32_16x16x32_bf16 v[80:83], v[170:173], v[194:197], 0
	v_mfma_f32_16x16x32_bf16 v[68:71], v[148:151], v[218:221], 0
	v_mfma_f32_16x16x32_bf16 v[64:67], v[170:173], v[218:221], 0
	v_mfma_f32_16x16x32_bf16 v[128:131], v[152:155], v[182:185], v[128:131]
	v_mfma_f32_16x16x32_bf16 v[124:127], v[174:177], v[182:185], v[124:127]
	v_mfma_f32_16x16x32_bf16 v[100:103], v[152:155], v[190:193], v[100:103]
	v_mfma_f32_16x16x32_bf16 v[96:99], v[174:177], v[190:193], v[96:99]
	v_mfma_f32_16x16x32_bf16 v[84:87], v[152:155], v[198:201], v[84:87]
	v_mfma_f32_16x16x32_bf16 v[80:83], v[174:177], v[198:201], v[80:83]
	v_mfma_f32_16x16x32_bf16 v[68:71], v[152:155], v[222:225], v[68:71]
	v_mfma_f32_16x16x32_bf16 v[64:67], v[174:177], v[222:225], v[64:67]
	s_setprio 0
	s_barrier
	s_add_i32 s68, s68, s31
	v_lshl_add_u64 v[238:239], s[24:25], 0, v[208:209]
	s_mov_b32 m0, s68
	ds_read_b128 v[178:181], v211 offset:16384
	ds_read_b128 v[182:185], v211 offset:17408
	ds_read_b128 v[186:189], v211 offset:18432
	ds_read_b128 v[190:193], v211 offset:19456
	ds_read_b128 v[194:197], v211 offset:20480
	ds_read_b128 v[198:201], v211 offset:21504
	ds_read_b128 v[218:221], v211 offset:22528
	ds_read_b128 v[222:225], v211 offset:23552
	global_load_lds_dwordx4 v[238:239], off
	s_add_i32 m0, s68, 0x2000
	s_add_u32 s68, s24, 0x40000
	v_lshl_add_u64 v[240:241], s[24:25], 0, v[156:157]
	s_addc_u32 s69, s25, 0
	s_add_i32 s70, s70, s31
	global_load_lds_dwordx4 v[240:241], off
	v_lshl_add_u64 v[242:243], s[68:69], 0, v[208:209]
	s_mov_b32 m0, s70
	s_nop 0
	global_load_lds_dwordx4 v[242:243], off
	v_lshl_add_u64 v[242:243], s[68:69], 0, v[156:157]
	s_add_i32 m0, s70, 0x2000
	s_nop 0
	global_load_lds_dwordx4 v[242:243], off
	v_lshl_add_u64 v[242:243], s[26:27], 0, v[160:161]
	s_mov_b32 m0, s35
	s_nop 0
	global_load_lds_dwordx4 v[242:243], off
	v_lshl_add_u64 v[242:243], s[26:27], 0, v[158:159]
	s_mov_b32 m0, s44
	s_nop 0
	global_load_lds_dwordx4 v[242:243], off
	s_waitcnt vmcnt(8)
	s_waitcnt lgkmcnt(0)
	s_barrier
; #define PG8_STAGE(bufoff, gbase, voff) do { _Pragma("unroll") for (int _i = 0; _i < 2; ++_i) \
;         __builtin_amdgcn_global_load_lds((const unsigned*)((const char*)(gbase) + (voff)[_i]), (PG8_LAS unsigned*)(lds + (bufoff) + ldsw + _i * 8192), 16, 0, 0); } while (0)
; #define PG8_LDA(dst, b, h) do { _Pragma("unroll") for (int m = 0; m < 4; ++m) _Pragma("unroll") for (int k = 0; k < 2; ++k) dst[m][k] = *(const PG8_LAS bf16x8*)(lds + PG8_SA(b, h) + aoff + m * 2048 + k * 1024); } while (0)
; #define PG8_LDB(dst, b, h) do { _Pragma("unroll") for (int n = 0; n < 2; ++n) _Pragma("unroll") for (int k = 0; k < 2; ++k) dst[n][k] = *(const PG8_LAS bf16x8*)(lds + PG8_SB(b, h) + boff + n * 2048 + k * 1024); } while (0)
; #define PG8_MMA(ai, bj, At, Bt) do { __builtin_amdgcn_s_setprio(1); _Pragma("unroll") for (int m = 0; m < 4; ++m) _Pragma("unroll") for (int n = 0; n < 2; ++n) _Pragma("unroll") for (int k = 0; k < 2; ++k) \
;         acc[ai][bj][m][n] = __builtin_amdgcn_mfma_f32_16x16x32_bf16(Bt[n][k], At[m][k], acc[ai][bj][m][n], 0, 0, 0); __builtin_amdgcn_s_setprio(0); } while (0)
; #define PG8_WAIT_V(n) asm volatile("s_waitcnt vmcnt(" #n ")" ::: "memory")
; #define PG8_WAIT_L(n) asm volatile("s_waitcnt lgkmcnt(" #n ")" ::: "memory")
; #define PG8_BAR __builtin_amdgcn_s_barrier()
; #define PG8_SCHED __builtin_amdgcn_sched_barrier(0)
;     ...
;             PG8_WAIT_V(8); PG8_WAIT_L(0); PG8_BAR; PG8_MMA(1, 0, At, B0); PG8_MMA(1, 1, At, B1); PG8_BAR; PG8_SCHED;
;             PG8_LDB(B0, 1, 0); PG8_LDB(B1, 1, 1); PG8_SCHED; PG8_LDA(At, 1, 0); PG8_STAGE(PG8_SA(0, 1), a2 + hstepA, voffA);
;             PG8_WAIT_V(8); PG8_WAIT_L(0); PG8_BAR; PG8_MMA(0, 0, At, B0); PG8_MMA(0, 1, At, B1); PG8_BAR; PG8_SCHED;
	s_setprio 1
	s_waitcnt lgkmcnt(0)
	v_mfma_f32_16x16x32_bf16 v[60:63], v[132:135], v[178:181], 0
	v_mfma_f32_16x16x32_bf16 v[56:59], v[140:143], v[178:181], 0
	v_mfma_f32_16x16x32_bf16 v[44:47], v[132:135], v[186:189], 0
	v_mfma_f32_16x16x32_bf16 v[40:43], v[140:143], v[186:189], 0
	v_mfma_f32_16x16x32_bf16 v[28:31], v[132:135], v[194:197], 0
	v_mfma_f32_16x16x32_bf16 v[24:27], v[140:143], v[194:197], 0
	v_mfma_f32_16x16x32_bf16 v[12:15], v[132:135], v[218:221], 0
	v_mfma_f32_16x16x32_bf16 v[8:11], v[140:143], v[218:221], 0
	v_mfma_f32_16x16x32_bf16 v[60:63], v[136:139], v[182:185], v[60:63]
	v_mfma_f32_16x16x32_bf16 v[56:59], v[144:147], v[182:185], v[56:59]
	v_mfma_f32_16x16x32_bf16 v[44:47], v[136:139], v[190:193], v[44:47]
	v_mfma_f32_16x16x32_bf16 v[40:43], v[144:147], v[190:193], v[40:43]
	v_mfma_f32_16x16x32_bf16 v[28:31], v[136:139], v[198:201], v[28:31]
	v_mfma_f32_16x16x32_bf16 v[24:27], v[144:147], v[198:201], v[24:27]
	v_mfma_f32_16x16x32_bf16 v[12:15], v[136:139], v[222:225], v[12:15]
	v_mfma_f32_16x16x32_bf16 v[8:11], v[144:147], v[222:225], v[8:11]
	s_setprio 0
	s_setprio 1
	v_mfma_f32_16x16x32_bf16 v[52:55], v[148:151], v[178:181], 0
	v_mfma_f32_16x16x32_bf16 v[48:51], v[170:173], v[178:181], 0
	v_mfma_f32_16x16x32_bf16 v[36:39], v[148:151], v[186:189], 0
	v_mfma_f32_16x16x32_bf16 v[32:35], v[170:173], v[186:189], 0
	v_mfma_f32_16x16x32_bf16 v[20:23], v[148:151], v[194:197], 0
	v_mfma_f32_16x16x32_bf16 v[16:19], v[170:173], v[194:197], 0
	v_mfma_f32_16x16x32_bf16 v[4:7], v[148:151], v[218:221], 0
	v_mfma_f32_16x16x32_bf16 v[0:3], v[170:173], v[218:221], 0
	v_mfma_f32_16x16x32_bf16 v[52:55], v[152:155], v[182:185], v[52:55]
	v_mfma_f32_16x16x32_bf16 v[48:51], v[174:177], v[182:185], v[48:51]
	v_mfma_f32_16x16x32_bf16 v[36:39], v[152:155], v[190:193], v[36:39]
	v_mfma_f32_16x16x32_bf16 v[32:35], v[174:177], v[190:193], v[32:35]
	v_mfma_f32_16x16x32_bf16 v[20:23], v[152:155], v[198:201], v[20:23]
	v_mfma_f32_16x16x32_bf16 v[16:19], v[174:177], v[198:201], v[16:19]
	v_mfma_f32_16x16x32_bf16 v[4:7], v[152:155], v[222:225], v[4:7]
	v_mfma_f32_16x16x32_bf16 v[0:3], v[174:177], v[222:225], v[0:3]
	s_setprio 0
	s_barrier
	s_add_i32 s68, 0, 0x18000
	s_add_i32 s69, 0, 0x1c000
	v_add_u32_e32 v144, s68, v203
	v_add_u32_e32 v174, s69, v203
	ds_read_b128 v[132:135], v144
	ds_read_b128 v[136:139], v144 offset:1024
	ds_read_b128 v[140:143], v144 offset:2048
	ds_read_b128 v[144:147], v144 offset:3072
	ds_read_b128 v[148:151], v174
	ds_read_b128 v[152:155], v174 offset:1024
	ds_read_b128 v[170:173], v174 offset:2048
	ds_read_b128 v[174:177], v174 offset:3072
	s_add_u32 s26, s26, 0x40000
	s_addc_u32 s27, s27, 0
	s_mov_b32 m0, s45
	v_lshl_add_u64 v[242:243], s[26:27], 0, v[160:161]
	ds_read_b128 v[178:181], v211 offset:32768
	ds_read_b128 v[182:185], v211 offset:33792
	ds_read_b128 v[186:189], v211 offset:34816
	ds_read_b128 v[190:193], v211 offset:35840
	ds_read_b128 v[194:197], v211 offset:36864
	ds_read_b128 v[198:201], v211 offset:37888
	ds_read_b128 v[218:221], v211 offset:38912
	ds_read_b128 v[222:225], v211 offset:39936
	global_load_lds_dwordx4 v[242:243], off
	v_lshl_add_u64 v[242:243], s[26:27], 0, v[158:159]
	s_mov_b32 m0, s46
	s_nop 0
	global_load_lds_dwordx4 v[242:243], off
	s_waitcnt vmcnt(8)
	s_waitcnt lgkmcnt(0)
	s_barrier
	s_setprio 1
	s_waitcnt lgkmcnt(0)
	v_mfma_f32_16x16x32_bf16 v[120:123], v[132:135], v[178:181], v[120:123]
	v_mfma_f32_16x16x32_bf16 v[116:119], v[140:143], v[178:181], v[116:119]
	v_mfma_f32_16x16x32_bf16 v[108:111], v[132:135], v[186:189], v[108:111]
	v_mfma_f32_16x16x32_bf16 v[104:107], v[140:143], v[186:189], v[104:107]
	v_mfma_f32_16x16x32_bf16 v[92:95], v[132:135], v[194:197], v[92:95]
	v_mfma_f32_16x16x32_bf16 v[88:91], v[140:143], v[194:197], v[88:91]
	v_mfma_f32_16x16x32_bf16 v[76:79], v[132:135], v[218:221], v[76:79]
	v_mfma_f32_16x16x32_bf16 v[72:75], v[140:143], v[218:221], v[72:75]
	v_mfma_f32_16x16x32_bf16 v[120:123], v[136:139], v[182:185], v[120:123]
	v_mfma_f32_16x16x32_bf16 v[116:119], v[144:147], v[182:185], v[116:119]
	v_mfma_f32_16x16x32_bf16 v[108:111], v[136:139], v[190:193], v[108:111]
	v_mfma_f32_16x16x32_bf16 v[104:107], v[144:147], v[190:193], v[104:107]
	v_mfma_f32_16x16x32_bf16 v[92:95], v[136:139], v[198:201], v[92:95]
	v_mfma_f32_16x16x32_bf16 v[88:91], v[144:147], v[198:201], v[88:91]
	v_mfma_f32_16x16x32_bf16 v[76:79], v[136:139], v[222:225], v[76:79]
	v_mfma_f32_16x16x32_bf16 v[72:75], v[144:147], v[222:225], v[72:75]
	s_setprio 0
	s_setprio 1
	v_mfma_f32_16x16x32_bf16 v[128:131], v[148:151], v[178:181], v[128:131]
	v_mfma_f32_16x16x32_bf16 v[124:127], v[170:173], v[178:181], v[124:127]
	v_mfma_f32_16x16x32_bf16 v[100:103], v[148:151], v[186:189], v[100:103]
	v_mfma_f32_16x16x32_bf16 v[96:99], v[170:173], v[186:189], v[96:99]
	v_mfma_f32_16x16x32_bf16 v[84:87], v[148:151], v[194:197], v[84:87]
	v_mfma_f32_16x16x32_bf16 v[80:83], v[170:173], v[194:197], v[80:83]
	v_mfma_f32_16x16x32_bf16 v[68:71], v[148:151], v[218:221], v[68:71]
	v_mfma_f32_16x16x32_bf16 v[64:67], v[170:173], v[218:221], v[64:67]
	v_mfma_f32_16x16x32_bf16 v[128:131], v[152:155], v[182:185], v[128:131]
	v_mfma_f32_16x16x32_bf16 v[124:127], v[174:177], v[182:185], v[124:127]
	v_mfma_f32_16x16x32_bf16 v[100:103], v[152:155], v[190:193], v[100:103]
	v_mfma_f32_16x16x32_bf16 v[96:99], v[174:177], v[190:193], v[96:99]
	v_mfma_f32_16x16x32_bf16 v[84:87], v[152:155], v[198:201], v[84:87]
	v_mfma_f32_16x16x32_bf16 v[80:83], v[174:177], v[198:201], v[80:83]
	v_mfma_f32_16x16x32_bf16 v[68:71], v[152:155], v[222:225], v[68:71]
	v_mfma_f32_16x16x32_bf16 v[64:67], v[174:177], v[222:225], v[64:67]
	s_setprio 0
	s_barrier
; #define PG8_STAGE(bufoff, gbase, voff) do { _Pragma("unroll") for (int _i = 0; _i < 2; ++_i) \
;         __builtin_amdgcn_global_load_lds((const unsigned*)((const char*)(gbase) + (voff)[_i]), (PG8_LAS unsigned*)(lds + (bufoff) + ldsw + _i * 8192), 16, 0, 0); } while (0)
; #define PG8_LDA(dst, b, h) do { _Pragma("unroll") for (int m = 0; m < 4; ++m) _Pragma("unroll") for (int k = 0; k < 2; ++k) dst[m][k] = *(const PG8_LAS bf16x8*)(lds + PG8_SA(b, h) + aoff + m * 2048 + k * 1024); } while (0)
; #define PG8_MMA(ai, bj, At, Bt) do { __builtin_amdgcn_s_setprio(1); _Pragma("unroll") for (int m = 0; m < 4; ++m) _Pragma("unroll") for (int n = 0; n < 2; ++n) _Pragma("unroll") for (int k = 0; k < 2; ++k) \
;         acc[ai][bj][m][n] = __builtin_amdgcn_mfma_f32_16x16x32_bf16(Bt[n][k], At[m][k], acc[ai][bj][m][n], 0, 0, 0); __builtin_amdgcn_s_setprio(0); } while (0)
; #define PG8_WAIT_V(n) asm volatile("s_waitcnt vmcnt(" #n ")" ::: "memory")
; #define PG8_WAIT_L(n) asm volatile("s_waitcnt lgkmcnt(" #n ")" ::: "memory")
; #define PG8_BAR __builtin_amdgcn_s_barrier()
; #define PG8_SCHED __builtin_amdgcn_sched_barrier(0)
;     ...
;         for (int t = 0; t < nt; t += 2) {
;             const bool last = (t == nt - 2);
;     ...
;             PG8_LDA(At, 1, 1); PG8_STAGE(PG8_SB(1, 0), b3, voffB); PG8_STAGE(PG8_SB(1, 1), b3 + hstepB, voffB); PG8_STAGE(PG8_SA(1, 0), a3, voffA);
;             PG8_WAIT_V(8); PG8_WAIT_L(0); PG8_BAR; PG8_MMA(1, 0, At, B0); PG8_MMA(1, 1, At, B1); PG8_BAR; PG8_SCHED;
	s_add_i32 s26, s68, s31
	v_lshl_add_u64 v[238:239], v[238:239], 0, s[72:73]
	s_mov_b32 m0, s26
	ds_read_b128 v[178:181], v211 offset:49152
	ds_read_b128 v[182:185], v211 offset:50176
	ds_read_b128 v[186:189], v211 offset:51200
	ds_read_b128 v[190:193], v211 offset:52224
	ds_read_b128 v[194:197], v211 offset:53248
	ds_read_b128 v[198:201], v211 offset:54272
	ds_read_b128 v[218:221], v211 offset:55296
	ds_read_b128 v[222:225], v211 offset:56320
	global_load_lds_dwordx4 v[238:239], off
	s_add_i32 m0, s26, 0x2000
	s_add_u32 s24, s24, 0x40080
	v_lshl_add_u64 v[238:239], v[240:241], 0, s[72:73]
	s_addc_u32 s25, s25, 0
	s_add_i32 s26, s69, s31
	global_load_lds_dwordx4 v[238:239], off
	v_lshl_add_u64 v[238:239], s[24:25], 0, v[208:209]
	s_mov_b32 m0, s26
	s_nop 0
	global_load_lds_dwordx4 v[238:239], off
	v_lshl_add_u64 v[238:239], s[24:25], 0, v[156:157]
	s_add_i32 m0, s26, 0x2000
	s_nop 0
	global_load_lds_dwordx4 v[238:239], off
	v_lshl_add_u64 v[238:239], s[20:21], 0, v[160:161]
	s_mov_b32 m0, s47
	s_nop 0
	global_load_lds_dwordx4 v[238:239], off
	v_lshl_add_u64 v[238:239], s[20:21], 0, v[158:159]
	s_mov_b32 m0, s48
	s_nop 0
	global_load_lds_dwordx4 v[238:239], off
	s_waitcnt vmcnt(8)
	s_waitcnt lgkmcnt(0)
	s_barrier
	s_setprio 1
	s_waitcnt lgkmcnt(0)
	v_mfma_f32_16x16x32_bf16 v[60:63], v[132:135], v[178:181], v[60:63]
	v_mfma_f32_16x16x32_bf16 v[56:59], v[140:143], v[178:181], v[56:59]
	v_mfma_f32_16x16x32_bf16 v[44:47], v[132:135], v[186:189], v[44:47]
	v_mfma_f32_16x16x32_bf16 v[40:43], v[140:143], v[186:189], v[40:43]
	v_mfma_f32_16x16x32_bf16 v[28:31], v[132:135], v[194:197], v[28:31]
	v_mfma_f32_16x16x32_bf16 v[24:27], v[140:143], v[194:197], v[24:27]
	v_mfma_f32_16x16x32_bf16 v[12:15], v[132:135], v[218:221], v[12:15]
	v_mfma_f32_16x16x32_bf16 v[8:11], v[140:143], v[218:221], v[8:11]
	v_mfma_f32_16x16x32_bf16 v[60:63], v[136:139], v[182:185], v[60:63]
	v_mfma_f32_16x16x32_bf16 v[56:59], v[144:147], v[182:185], v[56:59]
	v_mfma_f32_16x16x32_bf16 v[44:47], v[136:139], v[190:193], v[44:47]
	v_mfma_f32_16x16x32_bf16 v[40:43], v[144:147], v[190:193], v[40:43]
	v_mfma_f32_16x16x32_bf16 v[28:31], v[136:139], v[198:201], v[28:31]
	v_mfma_f32_16x16x32_bf16 v[24:27], v[144:147], v[198:201], v[24:27]
	v_mfma_f32_16x16x32_bf16 v[12:15], v[136:139], v[222:225], v[12:15]
	v_mfma_f32_16x16x32_bf16 v[8:11], v[144:147], v[222:225], v[8:11]
	s_setprio 0
	s_setprio 1
	v_mfma_f32_16x16x32_bf16 v[52:55], v[148:151], v[178:181], v[52:55]
	v_mfma_f32_16x16x32_bf16 v[48:51], v[170:173], v[178:181], v[48:51]
	v_mfma_f32_16x16x32_bf16 v[36:39], v[148:151], v[186:189], v[36:39]
	v_mfma_f32_16x16x32_bf16 v[32:35], v[170:173], v[186:189], v[32:35]
	v_mfma_f32_16x16x32_bf16 v[20:23], v[148:151], v[194:197], v[20:23]
	v_mfma_f32_16x16x32_bf16 v[16:19], v[170:173], v[194:197], v[16:19]
	v_mfma_f32_16x16x32_bf16 v[4:7], v[148:151], v[218:221], v[4:7]
	v_mfma_f32_16x16x32_bf16 v[0:3], v[170:173], v[218:221], v[0:3]
	v_mfma_f32_16x16x32_bf16 v[52:55], v[152:155], v[182:185], v[52:55]
	v_mfma_f32_16x16x32_bf16 v[48:51], v[174:177], v[182:185], v[48:51]
	v_mfma_f32_16x16x32_bf16 v[36:39], v[152:155], v[190:193], v[36:39]
	v_mfma_f32_16x16x32_bf16 v[32:35], v[174:177], v[190:193], v[32:35]
	v_mfma_f32_16x16x32_bf16 v[20:23], v[152:155], v[198:201], v[20:23]
	v_mfma_f32_16x16x32_bf16 v[16:19], v[174:177], v[198:201], v[16:19]
	v_mfma_f32_16x16x32_bf16 v[4:7], v[152:155], v[222:225], v[4:7]
	v_mfma_f32_16x16x32_bf16 v[0:3], v[174:177], v[222:225], v[0:3]
	s_setprio 0
	s_barrier
	s_add_i32 s67, s67, 2
	s_add_u32 s18, s18, 0x100
	s_addc_u32 s19, s19, 0
	s_cmp_gt_u32 s67, 13
	s_cbranch_scc0 .LBB0_451
	s_branch .Lpeel_exit_451

; #define PG8_BAR __builtin_amdgcn_s_barrier()
;     ...
;         if (wr == 0) PG8_BAR;
;         if (!has_next && wmat && gtid * 128u < wbytes) asm volatile("global_load_dword %0, %1, off" : "+v"(warmm) : "v"(wmat + (size_t)gtid * 128u) : "memory");
.Lpeel_exit_451:
	s_and_b64 vcc, exec, s[16:17]
	s_cbranch_vccz .LBB0_473
	s_barrier
	s_nor_b64 s[20:21], s[36:37], s[40:41]
	s_and_saveexec_b64 s[18:19], s[20:21]
	s_cbranch_execnz .LBB0_474

;     __device__ __forceinline__ const char* tile(const Unit& u, int t) const { return A + (size_t)u.pm * 2 * hstep() + (size_t)t * (BK * 2); }
;     __device__ __forceinline__ const char* tile(const Unit& u, int t) const { return U + (long)(t >> 2) * xoff + (size_t)u.pn * (1024 * 512) + (size_t)u.pm * 2 * hstep() + (size_t)(t & 3) * (BK * 2); }
; #define PG8_STAGE(bufoff, gbase, voff) do { _Pragma("unroll") for (int _i = 0; _i < 2; ++_i) \
;         __builtin_amdgcn_global_load_lds((const unsigned*)((const char*)(gbase) + (voff)[_i]), (PG8_LAS unsigned*)(lds + (bufoff) + ldsw + _i * 8192), 16, 0, 0); } while (0)
; #define PG8_LDA(dst, b, h) do { _Pragma("unroll") for (int m = 0; m < 4; ++m) _Pragma("unroll") for (int k = 0; k < 2; ++k) dst[m][k] = *(const PG8_LAS bf16x8*)(lds + PG8_SA(b, h) + aoff + m * 2048 + k * 1024); } while (0)
; #define PG8_LDB(dst, b, h) do { _Pragma("unroll") for (int n = 0; n < 2; ++n) _Pragma("unroll") for (int k = 0; k < 2; ++k) dst[n][k] = *(const PG8_LAS bf16x8*)(lds + PG8_SB(b, h) + boff + n * 2048 + k * 1024); } while (0)
; #define PG8_WAIT_V(n) asm volatile("s_waitcnt vmcnt(" #n ")" ::: "memory")
; #define PG8_WAIT_L(n) asm volatile("s_waitcnt lgkmcnt(" #n ")" ::: "memory")
; #define PG8_BAR __builtin_amdgcn_s_barrier()
; #define PG8_SCHED __builtin_amdgcn_sched_barrier(0)
;     ...
;         const bool has_next = S.next(ui + 1, nxt);
;         const Unit nu = has_next ? nxt : cur;
;         const char* nB = (const char*)g.Bt + (size_t)nu.pn * 2 * hstepB;
; #pragma unroll 1
;         for (int t = 0; t < nt; t += 2) {
;             const bool last = (t == nt - 2);
;             const char* a1 = AS.tile(cur, t + 1);
;             const char* a2 = last ? AS.tile(nu, 0) : AS.tile(cur, t + 2); const char* b2 = last ? nB : cB + (size_t)(t + 2) * kstep;
;             const char* a3 = last ? AS.tile(nu, 1) : AS.tile(cur, t + 3); const char* b3 = b2 + kstep;
;             PG8_LDB(B0, 0, 0); PG8_LDB(B1, 0, 1); PG8_SCHED; PG8_LDA(At, 0, 0); PG8_STAGE(PG8_SA(1, 1), a1 + hstepA, voffA);
;             PG8_WAIT_V(8); PG8_WAIT_L(0); PG8_BAR; PG8_MMA(0, 0, At, B0); PG8_MMA(0, 1, At, B1); PG8_BAR; PG8_SCHED;
;             PG8_LDA(At, 0, 1); PG8_STAGE(PG8_SB(0, 0), b2, voffB); PG8_STAGE(PG8_SB(0, 1), b2 + hstepB, voffB); PG8_STAGE(PG8_SA(0, 0), a2, voffA);
.LBB0_503:
	s_and_b64 s[8:9], s[38:39], exec
	s_cselect_b32 s15, s44, s46
	s_cselect_b32 s14, s45, s10
	s_ashr_i64 s[8:9], s[14:15], 13
	s_and_b32 s8, s8, 0xfff80000
	s_add_u32 s47, s5, s8
	s_addc_u32 s48, s20, s9
	s_ashr_i32 s11, s10, 31
	s_mov_b32 s18, s97
	s_mov_b32 s19, s14
	s_lshl_b64 s[16:17], s[10:11], 19
	s_ashr_i64 s[14:15], s[18:19], 13
	s_add_u32 s11, s21, s14
	s_addc_u32 s49, s24, s15
	s_add_u32 s50, s11, 0x80
	s_addc_u32 s51, s49, 0
	v_readlane_b32 s14, v254, 33
	v_readlane_b32 s15, v254, 34
	s_add_u32 s52, s14, s16
	s_addc_u32 s53, s15, s17
	s_add_u32 s54, s35, s12
	v_lshl_add_u64 v[142:143], v[138:139], 0, s[16:17]
	v_lshl_add_u64 v[144:145], v[140:141], 0, s[16:17]
	s_addc_u32 s55, s42, s13
	s_mov_b32 s56, -2
	s_mov_b64 s[12:13], 0
	s_mov_b64 s[64:65], 0x80
.Lpeel_504:
	s_add_u32 s14, s52, s12
	s_addc_u32 s15, s53, s13
	s_add_u32 s18, s14, 0x400100
	s_addc_u32 s19, s15, 0
	s_add_u32 s16, s54, s12
	s_addc_u32 s17, s55, s13
	s_add_u32 s14, s14, 0x400180
	s_addc_u32 s15, s15, 0
	s_add_i32 s57, 0, 0x10000
	s_add_i32 s60, 0, 0x14000
	v_add_u32_e32 v146, s57, v149
	ds_read_b128 v[156:159], v146
	ds_read_b128 v[160:163], v146 offset:1024
	ds_read_b128 v[164:167], v146 offset:2048
	ds_read_b128 v[168:171], v146 offset:3072
	v_add_u32_e32 v146, s60, v149
	ds_read_b128 v[172:175], v146
	ds_read_b128 v[176:179], v146 offset:1024
	ds_read_b128 v[180:183], v146 offset:2048
	ds_read_b128 v[184:187], v146 offset:3072
	s_cmpk_eq_i32 s12, 0x700
	s_cselect_b32 s15, s51, s15
	s_cselect_b32 s14, s50, s14
	s_cselect_b32 s17, s48, s17
	s_cselect_b32 s16, s47, s16
	s_cselect_b32 s19, s49, s19
	s_cselect_b32 s18, s11, s18
	v_lshl_add_u64 v[146:147], v[142:143], 0, s[12:13]
	s_add_i32 m0, s26, 0xc000
	ds_read_b128 v[188:191], v152
	ds_read_b128 v[192:195], v152 offset:1024
	ds_read_b128 v[196:199], v152 offset:2048
	ds_read_b128 v[200:203], v152 offset:3072
	ds_read_b128 v[204:207], v152 offset:4096
	ds_read_b128 v[218:221], v152 offset:5120
	ds_read_b128 v[222:225], v152 offset:6144
	ds_read_b128 v[238:241], v152 offset:7168
	global_load_lds_dwordx4 v[146:147], off
	v_lshl_add_u64 v[146:147], v[144:145], 0, s[12:13]
	s_add_i32 m0, s26, 0xe000
	s_nop 0
	global_load_lds_dwordx4 v[146:147], off
	s_waitcnt vmcnt(8)
	s_waitcnt lgkmcnt(0)
	s_barrier
	s_setprio 1
	s_waitcnt lgkmcnt(0)
	v_mfma_f32_16x16x32_bf16 v[124:127], v[156:159], v[188:191], 0
	v_mfma_f32_16x16x32_bf16 v[120:123], v[164:167], v[188:191], 0
	v_mfma_f32_16x16x32_bf16 v[108:111], v[156:159], v[196:199], 0
	v_mfma_f32_16x16x32_bf16 v[104:107], v[164:167], v[196:199], 0
	v_mfma_f32_16x16x32_bf16 v[92:95], v[156:159], v[204:207], 0
	v_mfma_f32_16x16x32_bf16 v[88:91], v[164:167], v[204:207], 0
	v_mfma_f32_16x16x32_bf16 v[76:79], v[156:159], v[222:225], 0
	v_mfma_f32_16x16x32_bf16 v[72:75], v[164:167], v[222:225], 0
	v_mfma_f32_16x16x32_bf16 v[124:127], v[160:163], v[192:195], v[124:127]
	v_mfma_f32_16x16x32_bf16 v[120:123], v[168:171], v[192:195], v[120:123]
	v_mfma_f32_16x16x32_bf16 v[108:111], v[160:163], v[200:203], v[108:111]
	v_mfma_f32_16x16x32_bf16 v[104:107], v[168:171], v[200:203], v[104:107]
	v_mfma_f32_16x16x32_bf16 v[92:95], v[160:163], v[218:221], v[92:95]
	v_mfma_f32_16x16x32_bf16 v[88:91], v[168:171], v[218:221], v[88:91]
	v_mfma_f32_16x16x32_bf16 v[76:79], v[160:163], v[238:241], v[76:79]
	v_mfma_f32_16x16x32_bf16 v[72:75], v[168:171], v[238:241], v[72:75]
	s_setprio 0
	s_setprio 1
	v_mfma_f32_16x16x32_bf16 v[116:119], v[172:175], v[188:191], 0
	v_mfma_f32_16x16x32_bf16 v[112:115], v[180:183], v[188:191], 0
	v_mfma_f32_16x16x32_bf16 v[100:103], v[172:175], v[196:199], 0
	v_mfma_f32_16x16x32_bf16 v[96:99], v[180:183], v[196:199], 0
	v_mfma_f32_16x16x32_bf16 v[84:87], v[172:175], v[204:207], 0
	v_mfma_f32_16x16x32_bf16 v[80:83], v[180:183], v[204:207], 0
	v_mfma_f32_16x16x32_bf16 v[68:71], v[172:175], v[222:225], 0
	v_mfma_f32_16x16x32_bf16 v[64:67], v[180:183], v[222:225], 0
	v_mfma_f32_16x16x32_bf16 v[116:119], v[176:179], v[192:195], v[116:119]
	v_mfma_f32_16x16x32_bf16 v[112:115], v[184:187], v[192:195], v[112:115]
	v_mfma_f32_16x16x32_bf16 v[100:103], v[176:179], v[200:203], v[100:103]
	v_mfma_f32_16x16x32_bf16 v[96:99], v[184:187], v[200:203], v[96:99]
	v_mfma_f32_16x16x32_bf16 v[84:87], v[176:179], v[218:221], v[84:87]
	v_mfma_f32_16x16x32_bf16 v[80:83], v[184:187], v[218:221], v[80:83]
	v_mfma_f32_16x16x32_bf16 v[68:71], v[176:179], v[238:241], v[68:71]
	v_mfma_f32_16x16x32_bf16 v[64:67], v[184:187], v[238:241], v[64:67]
	s_setprio 0
	s_barrier
	s_add_i32 s57, s57, s25
	v_lshl_add_u64 v[146:147], s[16:17], 0, v[208:209]
	s_mov_b32 m0, s57
	ds_read_b128 v[188:191], v152 offset:16384
	ds_read_b128 v[192:195], v152 offset:17408
	ds_read_b128 v[196:199], v152 offset:18432
	ds_read_b128 v[200:203], v152 offset:19456
	ds_read_b128 v[204:207], v152 offset:20480
	ds_read_b128 v[218:221], v152 offset:21504
	ds_read_b128 v[222:225], v152 offset:22528
	ds_read_b128 v[238:241], v152 offset:23552
	global_load_lds_dwordx4 v[146:147], off
	s_add_i32 m0, s57, 0x2000
	s_add_u32 s58, s16, 0x40000
	v_lshl_add_u64 v[242:243], s[16:17], 0, v[128:129]
	s_addc_u32 s59, s17, 0
	s_add_i32 s57, s60, s25
	global_load_lds_dwordx4 v[242:243], off
	v_lshl_add_u64 v[244:245], s[58:59], 0, v[208:209]
	s_mov_b32 m0, s57
	s_nop 0
	global_load_lds_dwordx4 v[244:245], off
	v_lshl_add_u64 v[244:245], s[58:59], 0, v[128:129]
	s_add_i32 m0, s57, 0x2000
	s_nop 0
	global_load_lds_dwordx4 v[244:245], off
	v_lshl_add_u64 v[244:245], s[18:19], 0, v[132:133]
	s_mov_b32 m0, s26
	s_nop 0
	global_load_lds_dwordx4 v[244:245], off
	v_lshl_add_u64 v[244:245], s[18:19], 0, v[130:131]
	s_mov_b32 m0, s27
	s_nop 0
	global_load_lds_dwordx4 v[244:245], off
	s_waitcnt vmcnt(8)
	s_waitcnt lgkmcnt(0)
	s_barrier
; #define PG8_STAGE(bufoff, gbase, voff) do { _Pragma("unroll") for (int _i = 0; _i < 2; ++_i) \
;         __builtin_amdgcn_global_load_lds((const unsigned*)((const char*)(gbase) + (voff)[_i]), (PG8_LAS unsigned*)(lds + (bufoff) + ldsw + _i * 8192), 16, 0, 0); } while (0)
; #define PG8_LDA(dst, b, h) do { _Pragma("unroll") for (int m = 0; m < 4; ++m) _Pragma("unroll") for (int k = 0; k < 2; ++k) dst[m][k] = *(const PG8_LAS bf16x8*)(lds + PG8_SA(b, h) + aoff + m * 2048 + k * 1024); } while (0)
; #define PG8_LDB(dst, b, h) do { _Pragma("unroll") for (int n = 0; n < 2; ++n) _Pragma("unroll") for (int k = 0; k < 2; ++k) dst[n][k] = *(const PG8_LAS bf16x8*)(lds + PG8_SB(b, h) + boff + n * 2048 + k * 1024); } while (0)
; #define PG8_MMA(ai, bj, At, Bt) do { __builtin_amdgcn_s_setprio(1); _Pragma("unroll") for (int m = 0; m < 4; ++m) _Pragma("unroll") for (int n = 0; n < 2; ++n) _Pragma("unroll") for (int k = 0; k < 2; ++k) \
;         acc[ai][bj][m][n] = __builtin_amdgcn_mfma_f32_16x16x32_bf16(Bt[n][k], At[m][k], acc[ai][bj][m][n], 0, 0, 0); __builtin_amdgcn_s_setprio(0); } while (0)
; #define PG8_WAIT_V(n) asm volatile("s_waitcnt vmcnt(" #n ")" ::: "memory")
; #define PG8_WAIT_L(n) asm volatile("s_waitcnt lgkmcnt(" #n ")" ::: "memory")
; #define PG8_BAR __builtin_amdgcn_s_barrier()
; #define PG8_SCHED __builtin_amdgcn_sched_barrier(0)
;     ...
;             PG8_WAIT_V(8); PG8_WAIT_L(0); PG8_BAR; PG8_MMA(1, 0, At, B0); PG8_MMA(1, 1, At, B1); PG8_BAR; PG8_SCHED;
;             PG8_LDB(B0, 1, 0); PG8_LDB(B1, 1, 1); PG8_SCHED; PG8_LDA(At, 1, 0); PG8_STAGE(PG8_SA(0, 1), a2 + hstepA, voffA);
;             PG8_WAIT_V(8); PG8_WAIT_L(0); PG8_BAR; PG8_MMA(0, 0, At, B0); PG8_MMA(0, 1, At, B1); PG8_BAR; PG8_SCHED;
	s_setprio 1
	s_waitcnt lgkmcnt(0)
	v_mfma_f32_16x16x32_bf16 v[60:63], v[156:159], v[188:191], 0
	v_mfma_f32_16x16x32_bf16 v[56:59], v[164:167], v[188:191], 0
	v_mfma_f32_16x16x32_bf16 v[44:47], v[156:159], v[196:199], 0
	v_mfma_f32_16x16x32_bf16 v[40:43], v[164:167], v[196:199], 0
	v_mfma_f32_16x16x32_bf16 v[28:31], v[156:159], v[204:207], 0
	v_mfma_f32_16x16x32_bf16 v[24:27], v[164:167], v[204:207], 0
	v_mfma_f32_16x16x32_bf16 v[12:15], v[156:159], v[222:225], 0
	v_mfma_f32_16x16x32_bf16 v[8:11], v[164:167], v[222:225], 0
	v_mfma_f32_16x16x32_bf16 v[60:63], v[160:163], v[192:195], v[60:63]
	v_mfma_f32_16x16x32_bf16 v[56:59], v[168:171], v[192:195], v[56:59]
	v_mfma_f32_16x16x32_bf16 v[44:47], v[160:163], v[200:203], v[44:47]
	v_mfma_f32_16x16x32_bf16 v[40:43], v[168:171], v[200:203], v[40:43]
	v_mfma_f32_16x16x32_bf16 v[28:31], v[160:163], v[218:221], v[28:31]
	v_mfma_f32_16x16x32_bf16 v[24:27], v[168:171], v[218:221], v[24:27]
	v_mfma_f32_16x16x32_bf16 v[12:15], v[160:163], v[238:241], v[12:15]
	v_mfma_f32_16x16x32_bf16 v[8:11], v[168:171], v[238:241], v[8:11]
	s_setprio 0
	s_setprio 1
	v_mfma_f32_16x16x32_bf16 v[52:55], v[172:175], v[188:191], 0
	v_mfma_f32_16x16x32_bf16 v[48:51], v[180:183], v[188:191], 0
	v_mfma_f32_16x16x32_bf16 v[36:39], v[172:175], v[196:199], 0
	v_mfma_f32_16x16x32_bf16 v[32:35], v[180:183], v[196:199], 0
	v_mfma_f32_16x16x32_bf16 v[20:23], v[172:175], v[204:207], 0
	v_mfma_f32_16x16x32_bf16 v[16:19], v[180:183], v[204:207], 0
	v_mfma_f32_16x16x32_bf16 v[4:7], v[172:175], v[222:225], 0
	v_mfma_f32_16x16x32_bf16 v[0:3], v[180:183], v[222:225], 0
	v_mfma_f32_16x16x32_bf16 v[52:55], v[176:179], v[192:195], v[52:55]
	v_mfma_f32_16x16x32_bf16 v[48:51], v[184:187], v[192:195], v[48:51]
	v_mfma_f32_16x16x32_bf16 v[36:39], v[176:179], v[200:203], v[36:39]
	v_mfma_f32_16x16x32_bf16 v[32:35], v[184:187], v[200:203], v[32:35]
	v_mfma_f32_16x16x32_bf16 v[20:23], v[176:179], v[218:221], v[20:23]
	v_mfma_f32_16x16x32_bf16 v[16:19], v[184:187], v[218:221], v[16:19]
	v_mfma_f32_16x16x32_bf16 v[4:7], v[176:179], v[238:241], v[4:7]
	v_mfma_f32_16x16x32_bf16 v[0:3], v[184:187], v[238:241], v[0:3]
	s_setprio 0
	s_barrier
	s_add_i32 s57, 0, 0x18000
	v_add_u32_e32 v155, s57, v149
	s_add_i32 s58, 0, 0x1c000
	ds_read_b128 v[156:159], v155
	ds_read_b128 v[160:163], v155 offset:1024
	ds_read_b128 v[164:167], v155 offset:2048
	ds_read_b128 v[168:171], v155 offset:3072
	v_add_u32_e32 v155, s58, v149
	ds_read_b128 v[172:175], v155
	ds_read_b128 v[176:179], v155 offset:1024
	ds_read_b128 v[180:183], v155 offset:2048
	ds_read_b128 v[184:187], v155 offset:3072
	s_add_u32 s18, s18, 0x40000
	s_addc_u32 s19, s19, 0
	s_mov_b32 m0, s28
	v_lshl_add_u64 v[244:245], s[18:19], 0, v[132:133]
	ds_read_b128 v[188:191], v152 offset:32768
	ds_read_b128 v[192:195], v152 offset:33792
	ds_read_b128 v[196:199], v152 offset:34816
	ds_read_b128 v[200:203], v152 offset:35840
	ds_read_b128 v[204:207], v152 offset:36864
	ds_read_b128 v[218:221], v152 offset:37888
	ds_read_b128 v[222:225], v152 offset:38912
	ds_read_b128 v[238:241], v152 offset:39936
	global_load_lds_dwordx4 v[244:245], off
	v_lshl_add_u64 v[244:245], s[18:19], 0, v[130:131]
	s_mov_b32 m0, s29
	s_nop 0
	global_load_lds_dwordx4 v[244:245], off
	s_waitcnt vmcnt(8)
	s_waitcnt lgkmcnt(0)
	s_barrier
	s_setprio 1
	s_waitcnt lgkmcnt(0)
	v_mfma_f32_16x16x32_bf16 v[124:127], v[156:159], v[188:191], v[124:127]
	v_mfma_f32_16x16x32_bf16 v[120:123], v[164:167], v[188:191], v[120:123]
	v_mfma_f32_16x16x32_bf16 v[108:111], v[156:159], v[196:199], v[108:111]
	v_mfma_f32_16x16x32_bf16 v[104:107], v[164:167], v[196:199], v[104:107]
	v_mfma_f32_16x16x32_bf16 v[92:95], v[156:159], v[204:207], v[92:95]
	v_mfma_f32_16x16x32_bf16 v[88:91], v[164:167], v[204:207], v[88:91]
	v_mfma_f32_16x16x32_bf16 v[76:79], v[156:159], v[222:225], v[76:79]
	v_mfma_f32_16x16x32_bf16 v[72:75], v[164:167], v[222:225], v[72:75]
	v_mfma_f32_16x16x32_bf16 v[124:127], v[160:163], v[192:195], v[124:127]
	v_mfma_f32_16x16x32_bf16 v[120:123], v[168:171], v[192:195], v[120:123]
	v_mfma_f32_16x16x32_bf16 v[108:111], v[160:163], v[200:203], v[108:111]
	v_mfma_f32_16x16x32_bf16 v[104:107], v[168:171], v[200:203], v[104:107]
	v_mfma_f32_16x16x32_bf16 v[92:95], v[160:163], v[218:221], v[92:95]
	v_mfma_f32_16x16x32_bf16 v[88:91], v[168:171], v[218:221], v[88:91]
	v_mfma_f32_16x16x32_bf16 v[76:79], v[160:163], v[238:241], v[76:79]
	v_mfma_f32_16x16x32_bf16 v[72:75], v[168:171], v[238:241], v[72:75]
	s_setprio 0
	s_setprio 1
	v_mfma_f32_16x16x32_bf16 v[116:119], v[172:175], v[188:191], v[116:119]
	v_mfma_f32_16x16x32_bf16 v[112:115], v[180:183], v[188:191], v[112:115]
	v_mfma_f32_16x16x32_bf16 v[100:103], v[172:175], v[196:199], v[100:103]
	v_mfma_f32_16x16x32_bf16 v[96:99], v[180:183], v[196:199], v[96:99]
	v_mfma_f32_16x16x32_bf16 v[84:87], v[172:175], v[204:207], v[84:87]
	v_mfma_f32_16x16x32_bf16 v[80:83], v[180:183], v[204:207], v[80:83]
	v_mfma_f32_16x16x32_bf16 v[68:71], v[172:175], v[222:225], v[68:71]
	v_mfma_f32_16x16x32_bf16 v[64:67], v[180:183], v[222:225], v[64:67]
	v_mfma_f32_16x16x32_bf16 v[116:119], v[176:179], v[192:195], v[116:119]
	v_mfma_f32_16x16x32_bf16 v[112:115], v[184:187], v[192:195], v[112:115]
	v_mfma_f32_16x16x32_bf16 v[100:103], v[176:179], v[200:203], v[100:103]
	v_mfma_f32_16x16x32_bf16 v[96:99], v[184:187], v[200:203], v[96:99]
	v_mfma_f32_16x16x32_bf16 v[84:87], v[176:179], v[218:221], v[84:87]
	v_mfma_f32_16x16x32_bf16 v[80:83], v[184:187], v[218:221], v[80:83]
	v_mfma_f32_16x16x32_bf16 v[68:71], v[176:179], v[238:241], v[68:71]
	v_mfma_f32_16x16x32_bf16 v[64:67], v[184:187], v[238:241], v[64:67]
	s_setprio 0
	s_barrier
; #define PG8_STAGE(bufoff, gbase, voff) do { _Pragma("unroll") for (int _i = 0; _i < 2; ++_i) \
;         __builtin_amdgcn_global_load_lds((const unsigned*)((const char*)(gbase) + (voff)[_i]), (PG8_LAS unsigned*)(lds + (bufoff) + ldsw + _i * 8192), 16, 0, 0); } while (0)
; #define PG8_LDA(dst, b, h) do { _Pragma("unroll") for (int m = 0; m < 4; ++m) _Pragma("unroll") for (int k = 0; k < 2; ++k) dst[m][k] = *(const PG8_LAS bf16x8*)(lds + PG8_SA(b, h) + aoff + m * 2048 + k * 1024); } while (0)
; #define PG8_MMA(ai, bj, At, Bt) do { __builtin_amdgcn_s_setprio(1); _Pragma("unroll") for (int m = 0; m < 4; ++m) _Pragma("unroll") for (int n = 0; n < 2; ++n) _Pragma("unroll") for (int k = 0; k < 2; ++k) \
;         acc[ai][bj][m][n] = __builtin_amdgcn_mfma_f32_16x16x32_bf16(Bt[n][k], At[m][k], acc[ai][bj][m][n], 0, 0, 0); __builtin_amdgcn_s_setprio(0); } while (0)
; #define PG8_WAIT_V(n) asm volatile("s_waitcnt vmcnt(" #n ")" ::: "memory")
; #define PG8_WAIT_L(n) asm volatile("s_waitcnt lgkmcnt(" #n ")" ::: "memory")
; #define PG8_BAR __builtin_amdgcn_s_barrier()
; #define PG8_SCHED __builtin_amdgcn_sched_barrier(0)
;     ...
;         for (int t = 0; t < nt; t += 2) {
;             const bool last = (t == nt - 2);
;     ...
;             PG8_LDA(At, 1, 1); PG8_STAGE(PG8_SB(1, 0), b3, voffB); PG8_STAGE(PG8_SB(1, 1), b3 + hstepB, voffB); PG8_STAGE(PG8_SA(1, 0), a3, voffA);
;             PG8_WAIT_V(8); PG8_WAIT_L(0); PG8_BAR; PG8_MMA(1, 0, At, B0); PG8_MMA(1, 1, At, B1); PG8_BAR; PG8_SCHED;
	s_add_i32 s18, s57, s25
	v_lshl_add_u64 v[146:147], v[146:147], 0, s[64:65]
	s_mov_b32 m0, s18
	ds_read_b128 v[188:191], v152 offset:49152
	ds_read_b128 v[192:195], v152 offset:50176
	ds_read_b128 v[196:199], v152 offset:51200
	ds_read_b128 v[200:203], v152 offset:52224
	ds_read_b128 v[204:207], v152 offset:53248
	ds_read_b128 v[218:221], v152 offset:54272
	ds_read_b128 v[222:225], v152 offset:55296
	ds_read_b128 v[238:241], v152 offset:56320
	global_load_lds_dwordx4 v[146:147], off
	s_add_i32 m0, s18, 0x2000
	s_add_u32 s16, s16, 0x40080
	v_lshl_add_u64 v[146:147], v[242:243], 0, s[64:65]
	s_addc_u32 s17, s17, 0
	s_add_i32 s18, s58, s25
	global_load_lds_dwordx4 v[146:147], off
	v_lshl_add_u64 v[146:147], s[16:17], 0, v[208:209]
	s_mov_b32 m0, s18
	s_nop 0
	global_load_lds_dwordx4 v[146:147], off
	v_lshl_add_u64 v[146:147], s[16:17], 0, v[128:129]
	s_add_i32 m0, s18, 0x2000
	s_nop 0
	global_load_lds_dwordx4 v[146:147], off
	v_lshl_add_u64 v[146:147], s[14:15], 0, v[132:133]
	s_mov_b32 m0, s30
	s_nop 0
	global_load_lds_dwordx4 v[146:147], off
	v_lshl_add_u64 v[146:147], s[14:15], 0, v[130:131]
	s_mov_b32 m0, s31
	s_nop 0
	global_load_lds_dwordx4 v[146:147], off
	s_waitcnt vmcnt(8)
	s_waitcnt lgkmcnt(0)
	s_barrier
	s_setprio 1
	s_waitcnt lgkmcnt(0)
	v_mfma_f32_16x16x32_bf16 v[60:63], v[156:159], v[188:191], v[60:63]
	v_mfma_f32_16x16x32_bf16 v[56:59], v[164:167], v[188:191], v[56:59]
	v_mfma_f32_16x16x32_bf16 v[44:47], v[156:159], v[196:199], v[44:47]
	v_mfma_f32_16x16x32_bf16 v[40:43], v[164:167], v[196:199], v[40:43]
	v_mfma_f32_16x16x32_bf16 v[28:31], v[156:159], v[204:207], v[28:31]
	v_mfma_f32_16x16x32_bf16 v[24:27], v[164:167], v[204:207], v[24:27]
	v_mfma_f32_16x16x32_bf16 v[12:15], v[156:159], v[222:225], v[12:15]
	v_mfma_f32_16x16x32_bf16 v[8:11], v[164:167], v[222:225], v[8:11]
	v_mfma_f32_16x16x32_bf16 v[60:63], v[160:163], v[192:195], v[60:63]
	v_mfma_f32_16x16x32_bf16 v[56:59], v[168:171], v[192:195], v[56:59]
	v_mfma_f32_16x16x32_bf16 v[44:47], v[160:163], v[200:203], v[44:47]
	v_mfma_f32_16x16x32_bf16 v[40:43], v[168:171], v[200:203], v[40:43]
	v_mfma_f32_16x16x32_bf16 v[28:31], v[160:163], v[218:221], v[28:31]
	v_mfma_f32_16x16x32_bf16 v[24:27], v[168:171], v[218:221], v[24:27]
	v_mfma_f32_16x16x32_bf16 v[12:15], v[160:163], v[238:241], v[12:15]
	v_mfma_f32_16x16x32_bf16 v[8:11], v[168:171], v[238:241], v[8:11]
	s_setprio 0
	s_setprio 1
	v_mfma_f32_16x16x32_bf16 v[52:55], v[172:175], v[188:191], v[52:55]
	v_mfma_f32_16x16x32_bf16 v[48:51], v[180:183], v[188:191], v[48:51]
	v_mfma_f32_16x16x32_bf16 v[36:39], v[172:175], v[196:199], v[36:39]
	v_mfma_f32_16x16x32_bf16 v[32:35], v[180:183], v[196:199], v[32:35]
	v_mfma_f32_16x16x32_bf16 v[20:23], v[172:175], v[204:207], v[20:23]
	v_mfma_f32_16x16x32_bf16 v[16:19], v[180:183], v[204:207], v[16:19]
	v_mfma_f32_16x16x32_bf16 v[4:7], v[172:175], v[222:225], v[4:7]
	v_mfma_f32_16x16x32_bf16 v[0:3], v[180:183], v[222:225], v[0:3]
	v_mfma_f32_16x16x32_bf16 v[52:55], v[176:179], v[192:195], v[52:55]
	v_mfma_f32_16x16x32_bf16 v[48:51], v[184:187], v[192:195], v[48:51]
	v_mfma_f32_16x16x32_bf16 v[36:39], v[176:179], v[200:203], v[36:39]
	v_mfma_f32_16x16x32_bf16 v[32:35], v[184:187], v[200:203], v[32:35]
	v_mfma_f32_16x16x32_bf16 v[20:23], v[176:179], v[218:221], v[20:23]
	v_mfma_f32_16x16x32_bf16 v[16:19], v[184:187], v[218:221], v[16:19]
	v_mfma_f32_16x16x32_bf16 v[4:7], v[176:179], v[238:241], v[4:7]
	v_mfma_f32_16x16x32_bf16 v[0:3], v[184:187], v[238:241], v[0:3]
	s_setprio 0
	s_barrier
	s_add_i32 s56, s56, 2
	s_add_u32 s12, s12, 0x100
	s_addc_u32 s13, s13, 0
	s_cmp_gt_u32 s56, 13
	s_cbranch_scc0 .LBB0_504
	s_branch .Lpeel_exit_504

; #define PG8_BAR __builtin_amdgcn_s_barrier()
;     ...
;         if (wr == 0) PG8_BAR;
;         if (!has_next && wmat && gtid * 128u < wbytes) asm volatile("global_load_dword %0, %1, off" : "+v"(warmm) : "v"(wmat + (size_t)gtid * 128u) : "memory");
.Lpeel_exit_504:
	s_and_b64 vcc, exec, s[6:7]
	s_cbranch_vccz .LBB0_515
	s_barrier
	s_nor_b64 s[14:15], s[36:37], s[38:39]
	s_and_saveexec_b64 s[12:13], s[14:15]
	s_cbranch_execnz .LBB0_516

;     __device__ __forceinline__ const char* tile(const Unit& u, int t) const { return A + (size_t)u.pm * 2 * hstep() + (size_t)t * (BK * 2); }
;     __device__ __forceinline__ const char* tile(const Unit& u, int t) const { return U + (long)(t >> 2) * xoff + (size_t)u.pn * (1024 * 512) + (size_t)u.pm * 2 * hstep() + (size_t)(t & 3) * (BK * 2); }
; #define PG8_STAGE(bufoff, gbase, voff) do { _Pragma("unroll") for (int _i = 0; _i < 2; ++_i) \
;         __builtin_amdgcn_global_load_lds((const unsigned*)((const char*)(gbase) + (voff)[_i]), (PG8_LAS unsigned*)(lds + (bufoff) + ldsw + _i * 8192), 16, 0, 0); } while (0)
; #define PG8_LDA(dst, b, h) do { _Pragma("unroll") for (int m = 0; m < 4; ++m) _Pragma("unroll") for (int k = 0; k < 2; ++k) dst[m][k] = *(const PG8_LAS bf16x8*)(lds + PG8_SA(b, h) + aoff + m * 2048 + k * 1024); } while (0)
; #define PG8_LDB(dst, b, h) do { _Pragma("unroll") for (int n = 0; n < 2; ++n) _Pragma("unroll") for (int k = 0; k < 2; ++k) dst[n][k] = *(const PG8_LAS bf16x8*)(lds + PG8_SB(b, h) + boff + n * 2048 + k * 1024); } while (0)
; #define PG8_WAIT_V(n) asm volatile("s_waitcnt vmcnt(" #n ")" ::: "memory")
; #define PG8_WAIT_L(n) asm volatile("s_waitcnt lgkmcnt(" #n ")" ::: "memory")
; #define PG8_BAR __builtin_amdgcn_s_barrier()
; #define PG8_SCHED __builtin_amdgcn_sched_barrier(0)
;     ...
;         const bool has_next = S.next(ui + 1, nxt);
;         const Unit nu = has_next ? nxt : cur;
;         const char* nB = (const char*)g.Bt + (size_t)nu.pn * 2 * hstepB;
; #pragma unroll 1
;         for (int t = 0; t < nt; t += 2) {
;             const bool last = (t == nt - 2);
;             const char* a1 = AS.tile(cur, t + 1);
;             const char* a2 = last ? AS.tile(nu, 0) : AS.tile(cur, t + 2); const char* b2 = last ? nB : cB + (size_t)(t + 2) * kstep;
;             const char* a3 = last ? AS.tile(nu, 1) : AS.tile(cur, t + 3); const char* b3 = b2 + kstep;
;             PG8_LDB(B0, 0, 0); PG8_LDB(B1, 0, 1); PG8_SCHED; PG8_LDA(At, 0, 0); PG8_STAGE(PG8_SA(1, 1), a1 + hstepA, voffA);
;             PG8_WAIT_V(8); PG8_WAIT_L(0); PG8_BAR; PG8_MMA(0, 0, At, B0); PG8_MMA(0, 1, At, B1); PG8_BAR; PG8_SCHED;
;             PG8_LDA(At, 0, 1); PG8_STAGE(PG8_SB(0, 0), b2, voffB); PG8_STAGE(PG8_SB(0, 1), b2 + hstepB, voffB); PG8_STAGE(PG8_SA(0, 0), a2, voffA);
.LBB0_533:
	s_and_b64 s[16:17], s[38:39], exec
	s_cselect_b32 s21, s56, s58
	s_cselect_b32 s20, s57, s0
	s_ashr_i64 s[16:17], s[20:21], 31
	s_and_b32 s16, s16, -2
	s_lshl_b64 s[16:17], s[16:17], s52
	s_add_u32 s40, s26, s16
	s_addc_u32 s41, s27, s17
	s_ashr_i32 s1, s0, 31
	s_bfe_i64 s[20:21], s[20:21], 0x200000
	s_lshl_b64 s[68:69], s[0:1], s31
	s_lshl_b64 s[20:21], s[20:21], s31
	s_add_u32 s1, s29, s20
	s_addc_u32 s59, s30, s21
	s_add_u32 s60, s1, 0x80
	s_addc_u32 s61, s59, 0
	s_add_u32 s64, s28, s68
	s_addc_u32 s65, 0, s69
	s_add_u32 s66, s53, s2
	v_readlane_b32 s82, v254, 33
	s_mov_b32 s80, s74
	s_addc_u32 s67, s54, s3
	v_lshl_add_u64 v[64:65], v[204:205], 0, s[68:69]
	v_lshl_add_u64 v[66:67], v[206:207], 0, s[68:69]
	s_mov_b32 s2, 0
	s_waitcnt lgkmcnt(0)
	s_mov_b64 s[76:77], 0x80
	s_mov_b64 s[78:79], 0x100
	v_readlane_b32 s83, v254, 34
.Lpeel_534:
	s_add_i32 s68, s2, 2
	s_add_u32 s3, s82, s64
	s_addc_u32 s20, s83, s65
	s_add_u32 s69, s3, 0x100
	s_addc_u32 s21, s20, 0
	s_add_u32 s70, s82, s66
	s_addc_u32 s71, s83, s67
	s_add_u32 s72, s3, 0x180
	s_addc_u32 s3, s20, 0
	s_add_i32 s73, 0, 0x10000
	s_add_i32 s74, 0, 0x14000
	v_add_u32_e32 v108, s73, v212
	v_add_u32_e32 v152, s74, v212
	ds_read_b128 v[76:79], v108
	ds_read_b128 v[88:91], v108 offset:1024
	ds_read_b128 v[100:103], v108 offset:2048
	ds_read_b128 v[108:111], v108 offset:3072
	ds_read_b128 v[124:127], v152
	ds_read_b128 v[128:131], v152 offset:1024
	ds_read_b128 v[144:147], v152 offset:2048
	ds_read_b128 v[152:155], v152 offset:3072
	s_cmp_eq_u32 s51, s2
	s_cselect_b32 s2, s60, s72
	s_cselect_b32 s3, s61, s3
	s_cselect_b32 s71, s41, s71
	s_cselect_b32 s70, s40, s70
	s_cselect_b32 s21, s59, s21
	s_cselect_b32 s20, s1, s69
	v_lshl_add_u64 v[222:223], s[82:83], 0, v[64:65]
	s_add_i32 m0, s35, 0xc000
	ds_read_b128 v[156:159], v241
	ds_read_b128 v[168:171], v241 offset:1024
	ds_read_b128 v[172:175], v241 offset:2048
	ds_read_b128 v[176:179], v241 offset:3072
	ds_read_b128 v[180:183], v241 offset:4096
	ds_read_b128 v[184:187], v241 offset:5120
	ds_read_b128 v[188:191], v241 offset:6144
	ds_read_b128 v[218:221], v241 offset:7168
	global_load_lds_dwordx4 v[222:223], off
	v_lshl_add_u64 v[222:223], s[82:83], 0, v[66:67]
	s_add_i32 m0, s35, 0xe000
	s_nop 0
	global_load_lds_dwordx4 v[222:223], off
	s_waitcnt vmcnt(8)
	s_waitcnt lgkmcnt(0)
	s_barrier
	s_setprio 1
	s_waitcnt lgkmcnt(0)
	v_mfma_f32_16x16x32_bf16 v[164:167], v[76:79], v[156:159], 0
	v_mfma_f32_16x16x32_bf16 v[160:163], v[100:103], v[156:159], 0
	v_mfma_f32_16x16x32_bf16 v[136:139], v[76:79], v[172:175], 0
	v_mfma_f32_16x16x32_bf16 v[132:135], v[100:103], v[172:175], 0
	v_mfma_f32_16x16x32_bf16 v[112:115], v[76:79], v[180:183], 0
	v_mfma_f32_16x16x32_bf16 v[104:107], v[100:103], v[180:183], 0
	v_mfma_f32_16x16x32_bf16 v[84:87], v[76:79], v[188:191], 0
	v_mfma_f32_16x16x32_bf16 v[80:83], v[100:103], v[188:191], 0
	v_mfma_f32_16x16x32_bf16 v[164:167], v[88:91], v[168:171], v[164:167]
	v_mfma_f32_16x16x32_bf16 v[160:163], v[108:111], v[168:171], v[160:163]
	v_mfma_f32_16x16x32_bf16 v[136:139], v[88:91], v[176:179], v[136:139]
	v_mfma_f32_16x16x32_bf16 v[132:135], v[108:111], v[176:179], v[132:135]
	v_mfma_f32_16x16x32_bf16 v[112:115], v[88:91], v[184:187], v[112:115]
	v_mfma_f32_16x16x32_bf16 v[104:107], v[108:111], v[184:187], v[104:107]
	v_mfma_f32_16x16x32_bf16 v[84:87], v[88:91], v[218:221], v[84:87]
	v_mfma_f32_16x16x32_bf16 v[80:83], v[108:111], v[218:221], v[80:83]
	s_setprio 0
	s_setprio 1
	v_mfma_f32_16x16x32_bf16 v[148:151], v[124:127], v[156:159], 0
	v_mfma_f32_16x16x32_bf16 v[140:143], v[144:147], v[156:159], 0
	v_mfma_f32_16x16x32_bf16 v[120:123], v[124:127], v[172:175], 0
	v_mfma_f32_16x16x32_bf16 v[116:119], v[144:147], v[172:175], 0
	v_mfma_f32_16x16x32_bf16 v[96:99], v[124:127], v[180:183], 0
	v_mfma_f32_16x16x32_bf16 v[92:95], v[144:147], v[180:183], 0
	v_mfma_f32_16x16x32_bf16 v[72:75], v[124:127], v[188:191], 0
	v_mfma_f32_16x16x32_bf16 v[68:71], v[144:147], v[188:191], 0
	v_mfma_f32_16x16x32_bf16 v[148:151], v[128:131], v[168:171], v[148:151]
	v_mfma_f32_16x16x32_bf16 v[140:143], v[152:155], v[168:171], v[140:143]
	v_mfma_f32_16x16x32_bf16 v[120:123], v[128:131], v[176:179], v[120:123]
	v_mfma_f32_16x16x32_bf16 v[116:119], v[152:155], v[176:179], v[116:119]
	v_mfma_f32_16x16x32_bf16 v[96:99], v[128:131], v[184:187], v[96:99]
	v_mfma_f32_16x16x32_bf16 v[92:95], v[152:155], v[184:187], v[92:95]
	v_mfma_f32_16x16x32_bf16 v[72:75], v[128:131], v[218:221], v[72:75]
	v_mfma_f32_16x16x32_bf16 v[68:71], v[152:155], v[218:221], v[68:71]
	s_setprio 0
	s_barrier
	s_add_i32 s69, s73, s25
	v_lshl_add_u64 v[222:223], s[70:71], 0, v[196:197]
	s_mov_b32 m0, s69
	ds_read_b128 v[156:159], v241 offset:16384
	ds_read_b128 v[168:171], v241 offset:17408
	ds_read_b128 v[172:175], v241 offset:18432
	ds_read_b128 v[176:179], v241 offset:19456
	ds_read_b128 v[180:183], v241 offset:20480
	ds_read_b128 v[184:187], v241 offset:21504
	ds_read_b128 v[188:191], v241 offset:22528
	ds_read_b128 v[218:221], v241 offset:23552
	global_load_lds_dwordx4 v[222:223], off
	s_add_i32 m0, s69, 0x2000
	v_lshl_add_u64 v[224:225], s[70:71], 0, v[192:193]
	s_add_u32 s70, s70, s24
	s_addc_u32 s71, s71, 0
	s_add_i32 s69, s74, s25
	global_load_lds_dwordx4 v[224:225], off
	v_lshl_add_u64 v[244:245], s[70:71], 0, v[196:197]
	s_mov_b32 m0, s69
	v_lshl_add_u64 v[246:247], s[70:71], 0, v[192:193]
	global_load_lds_dwordx4 v[244:245], off
	s_add_i32 m0, s69, 0x2000
	v_lshl_add_u64 v[248:249], s[20:21], 0, v[198:199]
	global_load_lds_dwordx4 v[246:247], off
	s_mov_b32 m0, s35
	s_nop 0
	global_load_lds_dwordx4 v[248:249], off
	v_lshl_add_u64 v[248:249], s[20:21], 0, v[194:195]
	s_mov_b32 m0, s44
	s_nop 0
	global_load_lds_dwordx4 v[248:249], off
	s_waitcnt vmcnt(8)
	s_waitcnt lgkmcnt(0)
	s_barrier
; #define PG8_STAGE(bufoff, gbase, voff) do { _Pragma("unroll") for (int _i = 0; _i < 2; ++_i) \
;         __builtin_amdgcn_global_load_lds((const unsigned*)((const char*)(gbase) + (voff)[_i]), (PG8_LAS unsigned*)(lds + (bufoff) + ldsw + _i * 8192), 16, 0, 0); } while (0)
; #define PG8_LDA(dst, b, h) do { _Pragma("unroll") for (int m = 0; m < 4; ++m) _Pragma("unroll") for (int k = 0; k < 2; ++k) dst[m][k] = *(const PG8_LAS bf16x8*)(lds + PG8_SA(b, h) + aoff + m * 2048 + k * 1024); } while (0)
; #define PG8_LDB(dst, b, h) do { _Pragma("unroll") for (int n = 0; n < 2; ++n) _Pragma("unroll") for (int k = 0; k < 2; ++k) dst[n][k] = *(const PG8_LAS bf16x8*)(lds + PG8_SB(b, h) + boff + n * 2048 + k * 1024); } while (0)
; #define PG8_MMA(ai, bj, At, Bt) do { __builtin_amdgcn_s_setprio(1); _Pragma("unroll") for (int m = 0; m < 4; ++m) _Pragma("unroll") for (int n = 0; n < 2; ++n) _Pragma("unroll") for (int k = 0; k < 2; ++k) \
;         acc[ai][bj][m][n] = __builtin_amdgcn_mfma_f32_16x16x32_bf16(Bt[n][k], At[m][k], acc[ai][bj][m][n], 0, 0, 0); __builtin_amdgcn_s_setprio(0); } while (0)
; #define PG8_WAIT_V(n) asm volatile("s_waitcnt vmcnt(" #n ")" ::: "memory")
; #define PG8_WAIT_L(n) asm volatile("s_waitcnt lgkmcnt(" #n ")" ::: "memory")
; #define PG8_BAR __builtin_amdgcn_s_barrier()
; #define PG8_SCHED __builtin_amdgcn_sched_barrier(0)
;     ...
;             PG8_WAIT_V(8); PG8_WAIT_L(0); PG8_BAR; PG8_MMA(1, 0, At, B0); PG8_MMA(1, 1, At, B1); PG8_BAR; PG8_SCHED;
;             PG8_LDB(B0, 1, 0); PG8_LDB(B1, 1, 1); PG8_SCHED; PG8_LDA(At, 1, 0); PG8_STAGE(PG8_SA(0, 1), a2 + hstepA, voffA);
;             PG8_WAIT_V(8); PG8_WAIT_L(0); PG8_BAR; PG8_MMA(0, 0, At, B0); PG8_MMA(0, 1, At, B1); PG8_BAR; PG8_SCHED;
	s_setprio 1
	s_waitcnt lgkmcnt(0)
	v_mfma_f32_16x16x32_bf16 v[60:63], v[76:79], v[156:159], 0
	v_mfma_f32_16x16x32_bf16 v[56:59], v[100:103], v[156:159], 0
	v_mfma_f32_16x16x32_bf16 v[44:47], v[76:79], v[172:175], 0
	v_mfma_f32_16x16x32_bf16 v[40:43], v[100:103], v[172:175], 0
	v_mfma_f32_16x16x32_bf16 v[28:31], v[76:79], v[180:183], 0
	v_mfma_f32_16x16x32_bf16 v[24:27], v[100:103], v[180:183], 0
	v_mfma_f32_16x16x32_bf16 v[12:15], v[76:79], v[188:191], 0
	v_mfma_f32_16x16x32_bf16 v[8:11], v[100:103], v[188:191], 0
	v_mfma_f32_16x16x32_bf16 v[60:63], v[88:91], v[168:171], v[60:63]
	v_mfma_f32_16x16x32_bf16 v[56:59], v[108:111], v[168:171], v[56:59]
	v_mfma_f32_16x16x32_bf16 v[44:47], v[88:91], v[176:179], v[44:47]
	v_mfma_f32_16x16x32_bf16 v[40:43], v[108:111], v[176:179], v[40:43]
	v_mfma_f32_16x16x32_bf16 v[28:31], v[88:91], v[184:187], v[28:31]
	v_mfma_f32_16x16x32_bf16 v[24:27], v[108:111], v[184:187], v[24:27]
	v_mfma_f32_16x16x32_bf16 v[12:15], v[88:91], v[218:221], v[12:15]
	v_mfma_f32_16x16x32_bf16 v[8:11], v[108:111], v[218:221], v[8:11]
	s_setprio 0
	s_setprio 1
	v_mfma_f32_16x16x32_bf16 v[52:55], v[124:127], v[156:159], 0
	v_mfma_f32_16x16x32_bf16 v[48:51], v[144:147], v[156:159], 0
	v_mfma_f32_16x16x32_bf16 v[36:39], v[124:127], v[172:175], 0
	v_mfma_f32_16x16x32_bf16 v[32:35], v[144:147], v[172:175], 0
	v_mfma_f32_16x16x32_bf16 v[20:23], v[124:127], v[180:183], 0
	v_mfma_f32_16x16x32_bf16 v[16:19], v[144:147], v[180:183], 0
	v_mfma_f32_16x16x32_bf16 v[4:7], v[124:127], v[188:191], 0
	v_mfma_f32_16x16x32_bf16 v[0:3], v[144:147], v[188:191], 0
	v_mfma_f32_16x16x32_bf16 v[52:55], v[128:131], v[168:171], v[52:55]
	v_mfma_f32_16x16x32_bf16 v[48:51], v[152:155], v[168:171], v[48:51]
	v_mfma_f32_16x16x32_bf16 v[36:39], v[128:131], v[176:179], v[36:39]
	v_mfma_f32_16x16x32_bf16 v[32:35], v[152:155], v[176:179], v[32:35]
	v_mfma_f32_16x16x32_bf16 v[20:23], v[128:131], v[184:187], v[20:23]
	v_mfma_f32_16x16x32_bf16 v[16:19], v[152:155], v[184:187], v[16:19]
	v_mfma_f32_16x16x32_bf16 v[4:7], v[128:131], v[218:221], v[4:7]
	v_mfma_f32_16x16x32_bf16 v[0:3], v[152:155], v[218:221], v[0:3]
	s_setprio 0
	s_barrier
	s_add_i32 s69, 0, 0x18000
	s_add_i32 s70, 0, 0x1c000
	v_add_u32_e32 v108, s69, v212
	v_add_u32_e32 v152, s70, v212
	ds_read_b128 v[76:79], v108
	ds_read_b128 v[88:91], v108 offset:1024
	ds_read_b128 v[100:103], v108 offset:2048
	ds_read_b128 v[108:111], v108 offset:3072
	ds_read_b128 v[124:127], v152
	ds_read_b128 v[128:131], v152 offset:1024
	ds_read_b128 v[144:147], v152 offset:2048
	ds_read_b128 v[152:155], v152 offset:3072
	s_add_u32 s20, s20, s24
	s_addc_u32 s21, s21, 0
	s_mov_b32 m0, s45
	v_lshl_add_u64 v[248:249], s[20:21], 0, v[198:199]
	ds_read_b128 v[156:159], v241 offset:32768
	ds_read_b128 v[168:171], v241 offset:33792
	ds_read_b128 v[172:175], v241 offset:34816
	ds_read_b128 v[176:179], v241 offset:35840
	ds_read_b128 v[180:183], v241 offset:36864
	ds_read_b128 v[184:187], v241 offset:37888
	ds_read_b128 v[188:191], v241 offset:38912
	ds_read_b128 v[218:221], v241 offset:39936
	global_load_lds_dwordx4 v[248:249], off
	v_lshl_add_u64 v[248:249], s[20:21], 0, v[194:195]
	s_mov_b32 m0, s46
	s_nop 0
	global_load_lds_dwordx4 v[248:249], off
	s_waitcnt vmcnt(8)
	s_waitcnt lgkmcnt(0)
	s_barrier
	s_setprio 1
	s_waitcnt lgkmcnt(0)
	v_mfma_f32_16x16x32_bf16 v[164:167], v[76:79], v[156:159], v[164:167]
	v_mfma_f32_16x16x32_bf16 v[160:163], v[100:103], v[156:159], v[160:163]
	v_mfma_f32_16x16x32_bf16 v[136:139], v[76:79], v[172:175], v[136:139]
	v_mfma_f32_16x16x32_bf16 v[132:135], v[100:103], v[172:175], v[132:135]
	v_mfma_f32_16x16x32_bf16 v[112:115], v[76:79], v[180:183], v[112:115]
	v_mfma_f32_16x16x32_bf16 v[104:107], v[100:103], v[180:183], v[104:107]
	v_mfma_f32_16x16x32_bf16 v[84:87], v[76:79], v[188:191], v[84:87]
	v_mfma_f32_16x16x32_bf16 v[80:83], v[100:103], v[188:191], v[80:83]
	v_mfma_f32_16x16x32_bf16 v[164:167], v[88:91], v[168:171], v[164:167]
	v_mfma_f32_16x16x32_bf16 v[160:163], v[108:111], v[168:171], v[160:163]
	v_mfma_f32_16x16x32_bf16 v[136:139], v[88:91], v[176:179], v[136:139]
	v_mfma_f32_16x16x32_bf16 v[132:135], v[108:111], v[176:179], v[132:135]
	v_mfma_f32_16x16x32_bf16 v[112:115], v[88:91], v[184:187], v[112:115]
	v_mfma_f32_16x16x32_bf16 v[104:107], v[108:111], v[184:187], v[104:107]
	v_mfma_f32_16x16x32_bf16 v[84:87], v[88:91], v[218:221], v[84:87]
	v_mfma_f32_16x16x32_bf16 v[80:83], v[108:111], v[218:221], v[80:83]
	s_setprio 0
	s_setprio 1
	v_mfma_f32_16x16x32_bf16 v[148:151], v[124:127], v[156:159], v[148:151]
	v_mfma_f32_16x16x32_bf16 v[140:143], v[144:147], v[156:159], v[140:143]
	v_mfma_f32_16x16x32_bf16 v[120:123], v[124:127], v[172:175], v[120:123]
	v_mfma_f32_16x16x32_bf16 v[116:119], v[144:147], v[172:175], v[116:119]
	v_mfma_f32_16x16x32_bf16 v[96:99], v[124:127], v[180:183], v[96:99]
	v_mfma_f32_16x16x32_bf16 v[92:95], v[144:147], v[180:183], v[92:95]
	v_mfma_f32_16x16x32_bf16 v[72:75], v[124:127], v[188:191], v[72:75]
	v_mfma_f32_16x16x32_bf16 v[68:71], v[144:147], v[188:191], v[68:71]
	v_mfma_f32_16x16x32_bf16 v[148:151], v[128:131], v[168:171], v[148:151]
	v_mfma_f32_16x16x32_bf16 v[140:143], v[152:155], v[168:171], v[140:143]
	v_mfma_f32_16x16x32_bf16 v[120:123], v[128:131], v[176:179], v[120:123]
	v_mfma_f32_16x16x32_bf16 v[116:119], v[152:155], v[176:179], v[116:119]
	v_mfma_f32_16x16x32_bf16 v[96:99], v[128:131], v[184:187], v[96:99]
	v_mfma_f32_16x16x32_bf16 v[92:95], v[152:155], v[184:187], v[92:95]
	v_mfma_f32_16x16x32_bf16 v[72:75], v[128:131], v[218:221], v[72:75]
	v_mfma_f32_16x16x32_bf16 v[68:71], v[152:155], v[218:221], v[68:71]
	s_setprio 0
	s_barrier
; #define PG8_STAGE(bufoff, gbase, voff) do { _Pragma("unroll") for (int _i = 0; _i < 2; ++_i) \
;         __builtin_amdgcn_global_load_lds((const unsigned*)((const char*)(gbase) + (voff)[_i]), (PG8_LAS unsigned*)(lds + (bufoff) + ldsw + _i * 8192), 16, 0, 0); } while (0)
; #define PG8_LDA(dst, b, h) do { _Pragma("unroll") for (int m = 0; m < 4; ++m) _Pragma("unroll") for (int k = 0; k < 2; ++k) dst[m][k] = *(const PG8_LAS bf16x8*)(lds + PG8_SA(b, h) + aoff + m * 2048 + k * 1024); } while (0)
; #define PG8_MMA(ai, bj, At, Bt) do { __builtin_amdgcn_s_setprio(1); _Pragma("unroll") for (int m = 0; m < 4; ++m) _Pragma("unroll") for (int n = 0; n < 2; ++n) _Pragma("unroll") for (int k = 0; k < 2; ++k) \
;         acc[ai][bj][m][n] = __builtin_amdgcn_mfma_f32_16x16x32_bf16(Bt[n][k], At[m][k], acc[ai][bj][m][n], 0, 0, 0); __builtin_amdgcn_s_setprio(0); } while (0)
; #define PG8_WAIT_V(n) asm volatile("s_waitcnt vmcnt(" #n ")" ::: "memory")
; #define PG8_WAIT_L(n) asm volatile("s_waitcnt lgkmcnt(" #n ")" ::: "memory")
; #define PG8_BAR __builtin_amdgcn_s_barrier()
; #define PG8_SCHED __builtin_amdgcn_sched_barrier(0)
;     ...
;         for (int t = 0; t < nt; t += 2) {
;             const bool last = (t == nt - 2);
;     ...
;             PG8_LDA(At, 1, 1); PG8_STAGE(PG8_SB(1, 0), b3, voffB); PG8_STAGE(PG8_SB(1, 1), b3 + hstepB, voffB); PG8_STAGE(PG8_SA(1, 0), a3, voffA);
;             PG8_WAIT_V(8); PG8_WAIT_L(0); PG8_BAR; PG8_MMA(1, 0, At, B0); PG8_MMA(1, 1, At, B1); PG8_BAR; PG8_SCHED;
	s_add_i32 s20, s69, s25
	v_lshl_add_u64 v[222:223], v[222:223], 0, s[76:77]
	s_mov_b32 m0, s20
	ds_read_b128 v[156:159], v241 offset:49152
	ds_read_b128 v[168:171], v241 offset:50176
	ds_read_b128 v[172:175], v241 offset:51200
	ds_read_b128 v[176:179], v241 offset:52224
	ds_read_b128 v[180:183], v241 offset:53248
	ds_read_b128 v[184:187], v241 offset:54272
	ds_read_b128 v[188:191], v241 offset:55296
	ds_read_b128 v[218:221], v241 offset:56320
	global_load_lds_dwordx4 v[222:223], off
	v_lshl_add_u64 v[222:223], v[224:225], 0, s[76:77]
	s_add_i32 m0, s20, 0x2000
	s_add_i32 s20, s70, s25
	global_load_lds_dwordx4 v[222:223], off
	v_lshl_add_u64 v[222:223], v[244:245], 0, s[76:77]
	s_mov_b32 m0, s20
	s_nop 0
	global_load_lds_dwordx4 v[222:223], off
	v_lshl_add_u64 v[222:223], v[246:247], 0, s[76:77]
	s_add_i32 m0, s20, 0x2000
	s_nop 0
	global_load_lds_dwordx4 v[222:223], off
	v_lshl_add_u64 v[222:223], s[2:3], 0, v[198:199]
	s_mov_b32 m0, s47
	s_nop 0
	global_load_lds_dwordx4 v[222:223], off
	v_lshl_add_u64 v[222:223], s[2:3], 0, v[194:195]
	s_mov_b32 m0, s48
	s_nop 0
	global_load_lds_dwordx4 v[222:223], off
	s_waitcnt vmcnt(8)
	s_waitcnt lgkmcnt(0)
	s_barrier
	s_setprio 1
	s_waitcnt lgkmcnt(0)
	v_mfma_f32_16x16x32_bf16 v[60:63], v[76:79], v[156:159], v[60:63]
	v_mfma_f32_16x16x32_bf16 v[56:59], v[100:103], v[156:159], v[56:59]
	v_mfma_f32_16x16x32_bf16 v[44:47], v[76:79], v[172:175], v[44:47]
	v_mfma_f32_16x16x32_bf16 v[40:43], v[100:103], v[172:175], v[40:43]
	v_mfma_f32_16x16x32_bf16 v[28:31], v[76:79], v[180:183], v[28:31]
	v_mfma_f32_16x16x32_bf16 v[24:27], v[100:103], v[180:183], v[24:27]
	v_mfma_f32_16x16x32_bf16 v[12:15], v[76:79], v[188:191], v[12:15]
	v_mfma_f32_16x16x32_bf16 v[8:11], v[100:103], v[188:191], v[8:11]
	v_mfma_f32_16x16x32_bf16 v[60:63], v[88:91], v[168:171], v[60:63]
	v_mfma_f32_16x16x32_bf16 v[56:59], v[108:111], v[168:171], v[56:59]
	v_mfma_f32_16x16x32_bf16 v[44:47], v[88:91], v[176:179], v[44:47]
	v_mfma_f32_16x16x32_bf16 v[40:43], v[108:111], v[176:179], v[40:43]
	v_mfma_f32_16x16x32_bf16 v[28:31], v[88:91], v[184:187], v[28:31]
	v_mfma_f32_16x16x32_bf16 v[24:27], v[108:111], v[184:187], v[24:27]
	v_mfma_f32_16x16x32_bf16 v[12:15], v[88:91], v[218:221], v[12:15]
	v_mfma_f32_16x16x32_bf16 v[8:11], v[108:111], v[218:221], v[8:11]
	s_setprio 0
	s_setprio 1
	v_mfma_f32_16x16x32_bf16 v[52:55], v[124:127], v[156:159], v[52:55]
	v_mfma_f32_16x16x32_bf16 v[48:51], v[144:147], v[156:159], v[48:51]
	v_mfma_f32_16x16x32_bf16 v[36:39], v[124:127], v[172:175], v[36:39]
	v_mfma_f32_16x16x32_bf16 v[32:35], v[144:147], v[172:175], v[32:35]
	v_mfma_f32_16x16x32_bf16 v[20:23], v[124:127], v[180:183], v[20:23]
	v_mfma_f32_16x16x32_bf16 v[16:19], v[144:147], v[180:183], v[16:19]
	v_mfma_f32_16x16x32_bf16 v[4:7], v[124:127], v[188:191], v[4:7]
	v_mfma_f32_16x16x32_bf16 v[0:3], v[144:147], v[188:191], v[0:3]
	v_mfma_f32_16x16x32_bf16 v[52:55], v[128:131], v[168:171], v[52:55]
	v_mfma_f32_16x16x32_bf16 v[48:51], v[152:155], v[168:171], v[48:51]
	v_mfma_f32_16x16x32_bf16 v[36:39], v[128:131], v[176:179], v[36:39]
	v_mfma_f32_16x16x32_bf16 v[32:35], v[152:155], v[176:179], v[32:35]
	v_mfma_f32_16x16x32_bf16 v[20:23], v[128:131], v[184:187], v[20:23]
	v_mfma_f32_16x16x32_bf16 v[16:19], v[152:155], v[184:187], v[16:19]
	v_mfma_f32_16x16x32_bf16 v[4:7], v[128:131], v[218:221], v[4:7]
	v_mfma_f32_16x16x32_bf16 v[0:3], v[152:155], v[218:221], v[0:3]
	s_setprio 0
	s_barrier
	s_add_u32 s64, s64, 0x100
	s_addc_u32 s65, s65, 0
	s_add_u32 s66, s66, 0x100
	s_addc_u32 s67, s67, 0
	v_lshl_add_u64 v[64:65], v[64:65], 0, s[78:79]
	v_lshl_add_u64 v[66:67], v[66:67], 0, s[78:79]
	s_cmp_ge_u32 s68, s50
	s_mov_b32 s2, s68
	s_cbranch_scc0 .LBB0_534
	s_branch .Lpeel_exit_534

;     ...
;         if (!has_next && wmat && gtid * 128u < wbytes) asm volatile("global_load_dword %0, %1, off" : "+v"(warmm) : "v"(wmat + (size_t)gtid * 128u) : "memory");
.Lpeel_exit_534:
	s_and_b64 vcc, exec, s[12:13]
	s_cbranch_vccz .LBB0_541
	s_barrier
	s_nor_b64 s[20:21], s[14:15], s[38:39]
	s_and_saveexec_b64 s[2:3], s[20:21]
	s_cbranch_execnz .LBB0_542

;     __device__ __forceinline__ const char* tile(const Unit& u, int t) const { return A + (size_t)u.pm * 2 * hstep() + (size_t)t * (BK * 2); }
;     __device__ __forceinline__ const char* tile(const Unit& u, int t) const { return U + (long)(t >> 2) * xoff + (size_t)u.pn * (1024 * 512) + (size_t)u.pm * 2 * hstep() + (size_t)(t & 3) * (BK * 2); }
; #define PG8_STAGE(bufoff, gbase, voff) do { _Pragma("unroll") for (int _i = 0; _i < 2; ++_i) \
;         __builtin_amdgcn_global_load_lds((const unsigned*)((const char*)(gbase) + (voff)[_i]), (PG8_LAS unsigned*)(lds + (bufoff) + ldsw + _i * 8192), 16, 0, 0); } while (0)
; #define PG8_LDA(dst, b, h) do { _Pragma("unroll") for (int m = 0; m < 4; ++m) _Pragma("unroll") for (int k = 0; k < 2; ++k) dst[m][k] = *(const PG8_LAS bf16x8*)(lds + PG8_SA(b, h) + aoff + m * 2048 + k * 1024); } while (0)
; #define PG8_LDB(dst, b, h) do { _Pragma("unroll") for (int n = 0; n < 2; ++n) _Pragma("unroll") for (int k = 0; k < 2; ++k) dst[n][k] = *(const PG8_LAS bf16x8*)(lds + PG8_SB(b, h) + boff + n * 2048 + k * 1024); } while (0)
; #define PG8_WAIT_V(n) asm volatile("s_waitcnt vmcnt(" #n ")" ::: "memory")
; #define PG8_WAIT_L(n) asm volatile("s_waitcnt lgkmcnt(" #n ")" ::: "memory")
; #define PG8_BAR __builtin_amdgcn_s_barrier()
; #define PG8_SCHED __builtin_amdgcn_sched_barrier(0)
;     ...
;         const bool has_next = S.next(ui + 1, nxt);
;         const Unit nu = has_next ? nxt : cur;
;         const char* nB = (const char*)g.Bt + (size_t)nu.pn * 2 * hstepB;
; #pragma unroll 1
;         for (int t = 0; t < nt; t += 2) {
;             const bool last = (t == nt - 2);
;             const char* a1 = AS.tile(cur, t + 1);
;             const char* a2 = last ? AS.tile(nu, 0) : AS.tile(cur, t + 2); const char* b2 = last ? nB : cB + (size_t)(t + 2) * kstep;
;             const char* a3 = last ? AS.tile(nu, 1) : AS.tile(cur, t + 3); const char* b3 = b2 + kstep;
;             PG8_LDB(B0, 0, 0); PG8_LDB(B1, 0, 1); PG8_SCHED; PG8_LDA(At, 0, 0); PG8_STAGE(PG8_SA(1, 1), a1 + hstepA, voffA);
;             PG8_WAIT_V(8); PG8_WAIT_L(0); PG8_BAR; PG8_MMA(0, 0, At, B0); PG8_MMA(0, 1, At, B1); PG8_BAR; PG8_SCHED;
;             PG8_LDA(At, 0, 1); PG8_STAGE(PG8_SB(0, 0), b2, voffB); PG8_STAGE(PG8_SB(0, 1), b2 + hstepB, voffB); PG8_STAGE(PG8_SA(0, 0), a2, voffA);
.LBB0_701:
	s_and_b64 s[16:17], s[38:39], exec
	s_cselect_b32 s21, s59, s61
	s_cselect_b32 s20, s60, s18
	s_ashr_i64 s[16:17], s[20:21], 13
	s_and_b32 s16, s16, 0xfff80000
	s_add_u32 s1, s44, s16
	s_addc_u32 s28, s45, s17
	s_ashr_i32 s19, s18, 31
	s_mov_b32 s26, s97
	s_mov_b32 s27, s20
	s_lshl_b64 s[24:25], s[18:19], 19
	s_ashr_i64 s[20:21], s[26:27], 13
	s_add_u32 s19, s46, s20
	s_addc_u32 s29, s47, s21
	s_add_u32 s30, s19, 0x80
	s_addc_u32 s31, s29, 0
	v_readlane_b32 s20, v254, 33
	v_readlane_b32 s21, v254, 34
	s_add_u32 s40, s20, s24
	s_addc_u32 s41, s21, s25
	s_add_u32 s42, s35, s2
	v_lshl_add_u64 v[128:129], v[152:153], 0, s[24:25]
	v_lshl_add_u64 v[130:131], v[154:155], 0, s[24:25]
	s_addc_u32 s43, s56, s3
	s_mov_b32 s62, -2
	s_mov_b64 s[2:3], 0
	s_mov_b64 s[68:69], 0x80
.Lpeel_702:
	s_add_u32 s20, s40, s2
	s_addc_u32 s21, s41, s3
	s_add_u32 s26, s20, 0x400100
	s_addc_u32 s27, s21, 0
	s_add_u32 s24, s42, s2
	s_addc_u32 s25, s43, s3
	s_add_u32 s20, s20, 0x400180
	s_addc_u32 s21, s21, 0
	s_add_i32 s63, 0, 0x10000
	s_add_i32 s66, 0, 0x14000
	v_add_u32_e32 v156, s63, v185
	v_add_u32_e32 v172, s66, v185
	ds_read_b128 v[132:135], v156
	ds_read_b128 v[136:139], v156 offset:1024
	ds_read_b128 v[140:143], v156 offset:2048
	ds_read_b128 v[156:159], v156 offset:3072
	ds_read_b128 v[160:163], v172
	ds_read_b128 v[164:167], v172 offset:1024
	ds_read_b128 v[168:171], v172 offset:2048
	ds_read_b128 v[172:175], v172 offset:3072
	s_cmpk_eq_i32 s2, 0x700
	s_cselect_b32 s21, s31, s21
	s_cselect_b32 s20, s30, s20
	s_cselect_b32 s25, s28, s25
	s_cselect_b32 s24, s1, s24
	s_cselect_b32 s27, s29, s27
	s_cselect_b32 s26, s19, s26
	v_lshl_add_u64 v[238:239], v[128:129], 0, s[2:3]
	s_add_i32 m0, s49, 0xc000
	ds_read_b128 v[176:179], v190
	ds_read_b128 v[180:183], v190 offset:1024
	ds_read_b128 v[192:195], v190 offset:2048
	ds_read_b128 v[196:199], v190 offset:3072
	ds_read_b128 v[200:203], v190 offset:4096
	ds_read_b128 v[204:207], v190 offset:5120
	ds_read_b128 v[218:221], v190 offset:6144
	ds_read_b128 v[222:225], v190 offset:7168
	global_load_lds_dwordx4 v[238:239], off
	v_lshl_add_u64 v[238:239], v[130:131], 0, s[2:3]
	s_add_i32 m0, s49, 0xe000
	s_nop 0
	global_load_lds_dwordx4 v[238:239], off
	s_waitcnt vmcnt(8)
	s_waitcnt lgkmcnt(0)
	s_barrier
	s_setprio 1
	s_waitcnt lgkmcnt(0)
	v_mfma_f32_16x16x32_bf16 v[124:127], v[132:135], v[176:179], 0
	v_mfma_f32_16x16x32_bf16 v[120:123], v[140:143], v[176:179], 0
	v_mfma_f32_16x16x32_bf16 v[112:115], v[132:135], v[192:195], 0
	v_mfma_f32_16x16x32_bf16 v[104:107], v[140:143], v[192:195], 0
	v_mfma_f32_16x16x32_bf16 v[96:99], v[132:135], v[200:203], 0
	v_mfma_f32_16x16x32_bf16 v[88:91], v[140:143], v[200:203], 0
	v_mfma_f32_16x16x32_bf16 v[80:83], v[132:135], v[218:221], 0
	v_mfma_f32_16x16x32_bf16 v[72:75], v[140:143], v[218:221], 0
	v_mfma_f32_16x16x32_bf16 v[124:127], v[136:139], v[180:183], v[124:127]
	v_mfma_f32_16x16x32_bf16 v[120:123], v[156:159], v[180:183], v[120:123]
	v_mfma_f32_16x16x32_bf16 v[112:115], v[136:139], v[196:199], v[112:115]
	v_mfma_f32_16x16x32_bf16 v[104:107], v[156:159], v[196:199], v[104:107]
	v_mfma_f32_16x16x32_bf16 v[96:99], v[136:139], v[204:207], v[96:99]
	v_mfma_f32_16x16x32_bf16 v[88:91], v[156:159], v[204:207], v[88:91]
	v_mfma_f32_16x16x32_bf16 v[80:83], v[136:139], v[222:225], v[80:83]
	v_mfma_f32_16x16x32_bf16 v[72:75], v[156:159], v[222:225], v[72:75]
	s_setprio 0
	s_setprio 1
	v_mfma_f32_16x16x32_bf16 v[116:119], v[160:163], v[176:179], 0
	v_mfma_f32_16x16x32_bf16 v[108:111], v[168:171], v[176:179], 0
	v_mfma_f32_16x16x32_bf16 v[100:103], v[160:163], v[192:195], 0
	v_mfma_f32_16x16x32_bf16 v[92:95], v[168:171], v[192:195], 0
	v_mfma_f32_16x16x32_bf16 v[84:87], v[160:163], v[200:203], 0
	v_mfma_f32_16x16x32_bf16 v[76:79], v[168:171], v[200:203], 0
	v_mfma_f32_16x16x32_bf16 v[68:71], v[160:163], v[218:221], 0
	v_mfma_f32_16x16x32_bf16 v[64:67], v[168:171], v[218:221], 0
	v_mfma_f32_16x16x32_bf16 v[116:119], v[164:167], v[180:183], v[116:119]
	v_mfma_f32_16x16x32_bf16 v[108:111], v[172:175], v[180:183], v[108:111]
	v_mfma_f32_16x16x32_bf16 v[100:103], v[164:167], v[196:199], v[100:103]
	v_mfma_f32_16x16x32_bf16 v[92:95], v[172:175], v[196:199], v[92:95]
	v_mfma_f32_16x16x32_bf16 v[84:87], v[164:167], v[204:207], v[84:87]
	v_mfma_f32_16x16x32_bf16 v[76:79], v[172:175], v[204:207], v[76:79]
	v_mfma_f32_16x16x32_bf16 v[68:71], v[164:167], v[222:225], v[68:71]
	v_mfma_f32_16x16x32_bf16 v[64:67], v[172:175], v[222:225], v[64:67]
	s_setprio 0
	s_barrier
	s_add_i32 s63, s63, s48
	v_lshl_add_u64 v[238:239], s[24:25], 0, v[148:149]
	s_mov_b32 m0, s63
	ds_read_b128 v[176:179], v190 offset:16384
	ds_read_b128 v[180:183], v190 offset:17408
	ds_read_b128 v[192:195], v190 offset:18432
	ds_read_b128 v[196:199], v190 offset:19456
	ds_read_b128 v[200:203], v190 offset:20480
	ds_read_b128 v[204:207], v190 offset:21504
	ds_read_b128 v[218:221], v190 offset:22528
	ds_read_b128 v[222:225], v190 offset:23552
	global_load_lds_dwordx4 v[238:239], off
	s_add_i32 m0, s63, 0x2000
	s_add_u32 s64, s24, 0x40000
	v_lshl_add_u64 v[240:241], s[24:25], 0, v[144:145]
	s_addc_u32 s65, s25, 0
	s_add_i32 s63, s66, s48
	global_load_lds_dwordx4 v[240:241], off
	v_lshl_add_u64 v[242:243], s[64:65], 0, v[148:149]
	s_mov_b32 m0, s63
	s_nop 0
	global_load_lds_dwordx4 v[242:243], off
	v_lshl_add_u64 v[242:243], s[64:65], 0, v[144:145]
	s_add_i32 m0, s63, 0x2000
	s_nop 0
	global_load_lds_dwordx4 v[242:243], off
	v_lshl_add_u64 v[242:243], s[26:27], 0, v[150:151]
	s_mov_b32 m0, s49
	s_nop 0
	global_load_lds_dwordx4 v[242:243], off
	v_lshl_add_u64 v[242:243], s[26:27], 0, v[146:147]
	s_mov_b32 m0, s50
	s_nop 0
	global_load_lds_dwordx4 v[242:243], off
	s_waitcnt vmcnt(8)
	s_waitcnt lgkmcnt(0)
	s_barrier
; #define PG8_STAGE(bufoff, gbase, voff) do { _Pragma("unroll") for (int _i = 0; _i < 2; ++_i) \
;         __builtin_amdgcn_global_load_lds((const unsigned*)((const char*)(gbase) + (voff)[_i]), (PG8_LAS unsigned*)(lds + (bufoff) + ldsw + _i * 8192), 16, 0, 0); } while (0)
; #define PG8_LDA(dst, b, h) do { _Pragma("unroll") for (int m = 0; m < 4; ++m) _Pragma("unroll") for (int k = 0; k < 2; ++k) dst[m][k] = *(const PG8_LAS bf16x8*)(lds + PG8_SA(b, h) + aoff + m * 2048 + k * 1024); } while (0)
; #define PG8_LDB(dst, b, h) do { _Pragma("unroll") for (int n = 0; n < 2; ++n) _Pragma("unroll") for (int k = 0; k < 2; ++k) dst[n][k] = *(const PG8_LAS bf16x8*)(lds + PG8_SB(b, h) + boff + n * 2048 + k * 1024); } while (0)
; #define PG8_MMA(ai, bj, At, Bt) do { __builtin_amdgcn_s_setprio(1); _Pragma("unroll") for (int m = 0; m < 4; ++m) _Pragma("unroll") for (int n = 0; n < 2; ++n) _Pragma("unroll") for (int k = 0; k < 2; ++k) \
;         acc[ai][bj][m][n] = __builtin_amdgcn_mfma_f32_16x16x32_bf16(Bt[n][k], At[m][k], acc[ai][bj][m][n], 0, 0, 0); __builtin_amdgcn_s_setprio(0); } while (0)
; #define PG8_WAIT_V(n) asm volatile("s_waitcnt vmcnt(" #n ")" ::: "memory")
; #define PG8_WAIT_L(n) asm volatile("s_waitcnt lgkmcnt(" #n ")" ::: "memory")
; #define PG8_BAR __builtin_amdgcn_s_barrier()
; #define PG8_SCHED __builtin_amdgcn_sched_barrier(0)
;     ...
;             PG8_WAIT_V(8); PG8_WAIT_L(0); PG8_BAR; PG8_MMA(1, 0, At, B0); PG8_MMA(1, 1, At, B1); PG8_BAR; PG8_SCHED;
;             PG8_LDB(B0, 1, 0); PG8_LDB(B1, 1, 1); PG8_SCHED; PG8_LDA(At, 1, 0); PG8_STAGE(PG8_SA(0, 1), a2 + hstepA, voffA);
;             PG8_WAIT_V(8); PG8_WAIT_L(0); PG8_BAR; PG8_MMA(0, 0, At, B0); PG8_MMA(0, 1, At, B1); PG8_BAR; PG8_SCHED;
	s_setprio 1
	s_waitcnt lgkmcnt(0)
	v_mfma_f32_16x16x32_bf16 v[60:63], v[132:135], v[176:179], 0
	v_mfma_f32_16x16x32_bf16 v[56:59], v[140:143], v[176:179], 0
	v_mfma_f32_16x16x32_bf16 v[48:51], v[132:135], v[192:195], 0
	v_mfma_f32_16x16x32_bf16 v[40:43], v[140:143], v[192:195], 0
	v_mfma_f32_16x16x32_bf16 v[32:35], v[132:135], v[200:203], 0
	v_mfma_f32_16x16x32_bf16 v[24:27], v[140:143], v[200:203], 0
	v_mfma_f32_16x16x32_bf16 v[16:19], v[132:135], v[218:221], 0
	v_mfma_f32_16x16x32_bf16 v[8:11], v[140:143], v[218:221], 0
	v_mfma_f32_16x16x32_bf16 v[60:63], v[136:139], v[180:183], v[60:63]
	v_mfma_f32_16x16x32_bf16 v[56:59], v[156:159], v[180:183], v[56:59]
	v_mfma_f32_16x16x32_bf16 v[48:51], v[136:139], v[196:199], v[48:51]
	v_mfma_f32_16x16x32_bf16 v[40:43], v[156:159], v[196:199], v[40:43]
	v_mfma_f32_16x16x32_bf16 v[32:35], v[136:139], v[204:207], v[32:35]
	v_mfma_f32_16x16x32_bf16 v[24:27], v[156:159], v[204:207], v[24:27]
	v_mfma_f32_16x16x32_bf16 v[16:19], v[136:139], v[222:225], v[16:19]
	v_mfma_f32_16x16x32_bf16 v[8:11], v[156:159], v[222:225], v[8:11]
	s_setprio 0
	s_setprio 1
	v_mfma_f32_16x16x32_bf16 v[52:55], v[160:163], v[176:179], 0
	v_mfma_f32_16x16x32_bf16 v[44:47], v[168:171], v[176:179], 0
	v_mfma_f32_16x16x32_bf16 v[36:39], v[160:163], v[192:195], 0
	v_mfma_f32_16x16x32_bf16 v[28:31], v[168:171], v[192:195], 0
	v_mfma_f32_16x16x32_bf16 v[20:23], v[160:163], v[200:203], 0
	v_mfma_f32_16x16x32_bf16 v[12:15], v[168:171], v[200:203], 0
	v_mfma_f32_16x16x32_bf16 v[4:7], v[160:163], v[218:221], 0
	v_mfma_f32_16x16x32_bf16 v[0:3], v[168:171], v[218:221], 0
	v_mfma_f32_16x16x32_bf16 v[52:55], v[164:167], v[180:183], v[52:55]
	v_mfma_f32_16x16x32_bf16 v[44:47], v[172:175], v[180:183], v[44:47]
	v_mfma_f32_16x16x32_bf16 v[36:39], v[164:167], v[196:199], v[36:39]
	v_mfma_f32_16x16x32_bf16 v[28:31], v[172:175], v[196:199], v[28:31]
	v_mfma_f32_16x16x32_bf16 v[20:23], v[164:167], v[204:207], v[20:23]
	v_mfma_f32_16x16x32_bf16 v[12:15], v[172:175], v[204:207], v[12:15]
	v_mfma_f32_16x16x32_bf16 v[4:7], v[164:167], v[222:225], v[4:7]
	v_mfma_f32_16x16x32_bf16 v[0:3], v[172:175], v[222:225], v[0:3]
	s_setprio 0
	s_barrier
	s_add_i32 s63, 0, 0x18000
	s_add_i32 s64, 0, 0x1c000
	v_add_u32_e32 v156, s63, v185
	v_add_u32_e32 v172, s64, v185
	ds_read_b128 v[132:135], v156
	ds_read_b128 v[136:139], v156 offset:1024
	ds_read_b128 v[140:143], v156 offset:2048
	ds_read_b128 v[156:159], v156 offset:3072
	ds_read_b128 v[160:163], v172
	ds_read_b128 v[164:167], v172 offset:1024
	ds_read_b128 v[168:171], v172 offset:2048
	ds_read_b128 v[172:175], v172 offset:3072
	s_add_u32 s26, s26, 0x40000
	s_addc_u32 s27, s27, 0
	s_mov_b32 m0, s51
	v_lshl_add_u64 v[242:243], s[26:27], 0, v[150:151]
	ds_read_b128 v[176:179], v190 offset:32768
	ds_read_b128 v[180:183], v190 offset:33792
	ds_read_b128 v[192:195], v190 offset:34816
	ds_read_b128 v[196:199], v190 offset:35840
	ds_read_b128 v[200:203], v190 offset:36864
	ds_read_b128 v[204:207], v190 offset:37888
	ds_read_b128 v[218:221], v190 offset:38912
	ds_read_b128 v[222:225], v190 offset:39936
	global_load_lds_dwordx4 v[242:243], off
	v_lshl_add_u64 v[242:243], s[26:27], 0, v[146:147]
	s_mov_b32 m0, s52
	s_nop 0
	global_load_lds_dwordx4 v[242:243], off
	s_waitcnt vmcnt(8)
	s_waitcnt lgkmcnt(0)
	s_barrier
	s_setprio 1
	s_waitcnt lgkmcnt(0)
	v_mfma_f32_16x16x32_bf16 v[124:127], v[132:135], v[176:179], v[124:127]
	v_mfma_f32_16x16x32_bf16 v[120:123], v[140:143], v[176:179], v[120:123]
	v_mfma_f32_16x16x32_bf16 v[112:115], v[132:135], v[192:195], v[112:115]
	v_mfma_f32_16x16x32_bf16 v[104:107], v[140:143], v[192:195], v[104:107]
	v_mfma_f32_16x16x32_bf16 v[96:99], v[132:135], v[200:203], v[96:99]
	v_mfma_f32_16x16x32_bf16 v[88:91], v[140:143], v[200:203], v[88:91]
	v_mfma_f32_16x16x32_bf16 v[80:83], v[132:135], v[218:221], v[80:83]
	v_mfma_f32_16x16x32_bf16 v[72:75], v[140:143], v[218:221], v[72:75]
	v_mfma_f32_16x16x32_bf16 v[124:127], v[136:139], v[180:183], v[124:127]
	v_mfma_f32_16x16x32_bf16 v[120:123], v[156:159], v[180:183], v[120:123]
	v_mfma_f32_16x16x32_bf16 v[112:115], v[136:139], v[196:199], v[112:115]
	v_mfma_f32_16x16x32_bf16 v[104:107], v[156:159], v[196:199], v[104:107]
	v_mfma_f32_16x16x32_bf16 v[96:99], v[136:139], v[204:207], v[96:99]
	v_mfma_f32_16x16x32_bf16 v[88:91], v[156:159], v[204:207], v[88:91]
	v_mfma_f32_16x16x32_bf16 v[80:83], v[136:139], v[222:225], v[80:83]
	v_mfma_f32_16x16x32_bf16 v[72:75], v[156:159], v[222:225], v[72:75]
	s_setprio 0
	s_setprio 1
	v_mfma_f32_16x16x32_bf16 v[116:119], v[160:163], v[176:179], v[116:119]
	v_mfma_f32_16x16x32_bf16 v[108:111], v[168:171], v[176:179], v[108:111]
	v_mfma_f32_16x16x32_bf16 v[100:103], v[160:163], v[192:195], v[100:103]
	v_mfma_f32_16x16x32_bf16 v[92:95], v[168:171], v[192:195], v[92:95]
	v_mfma_f32_16x16x32_bf16 v[84:87], v[160:163], v[200:203], v[84:87]
	v_mfma_f32_16x16x32_bf16 v[76:79], v[168:171], v[200:203], v[76:79]
	v_mfma_f32_16x16x32_bf16 v[68:71], v[160:163], v[218:221], v[68:71]
	v_mfma_f32_16x16x32_bf16 v[64:67], v[168:171], v[218:221], v[64:67]
	v_mfma_f32_16x16x32_bf16 v[116:119], v[164:167], v[180:183], v[116:119]
	v_mfma_f32_16x16x32_bf16 v[108:111], v[172:175], v[180:183], v[108:111]
	v_mfma_f32_16x16x32_bf16 v[100:103], v[164:167], v[196:199], v[100:103]
	v_mfma_f32_16x16x32_bf16 v[92:95], v[172:175], v[196:199], v[92:95]
	v_mfma_f32_16x16x32_bf16 v[84:87], v[164:167], v[204:207], v[84:87]
	v_mfma_f32_16x16x32_bf16 v[76:79], v[172:175], v[204:207], v[76:79]
	v_mfma_f32_16x16x32_bf16 v[68:71], v[164:167], v[222:225], v[68:71]
	v_mfma_f32_16x16x32_bf16 v[64:67], v[172:175], v[222:225], v[64:67]
	s_setprio 0
	s_barrier
; #define PG8_STAGE(bufoff, gbase, voff) do { _Pragma("unroll") for (int _i = 0; _i < 2; ++_i) \
;         __builtin_amdgcn_global_load_lds((const unsigned*)((const char*)(gbase) + (voff)[_i]), (PG8_LAS unsigned*)(lds + (bufoff) + ldsw + _i * 8192), 16, 0, 0); } while (0)
; #define PG8_LDA(dst, b, h) do { _Pragma("unroll") for (int m = 0; m < 4; ++m) _Pragma("unroll") for (int k = 0; k < 2; ++k) dst[m][k] = *(const PG8_LAS bf16x8*)(lds + PG8_SA(b, h) + aoff + m * 2048 + k * 1024); } while (0)
; #define PG8_MMA(ai, bj, At, Bt) do { __builtin_amdgcn_s_setprio(1); _Pragma("unroll") for (int m = 0; m < 4; ++m) _Pragma("unroll") for (int n = 0; n < 2; ++n) _Pragma("unroll") for (int k = 0; k < 2; ++k) \
;         acc[ai][bj][m][n] = __builtin_amdgcn_mfma_f32_16x16x32_bf16(Bt[n][k], At[m][k], acc[ai][bj][m][n], 0, 0, 0); __builtin_amdgcn_s_setprio(0); } while (0)
; #define PG8_WAIT_V(n) asm volatile("s_waitcnt vmcnt(" #n ")" ::: "memory")
; #define PG8_WAIT_L(n) asm volatile("s_waitcnt lgkmcnt(" #n ")" ::: "memory")
; #define PG8_BAR __builtin_amdgcn_s_barrier()
; #define PG8_SCHED __builtin_amdgcn_sched_barrier(0)
;     ...
;         for (int t = 0; t < nt; t += 2) {
;             const bool last = (t == nt - 2);
;     ...
;             PG8_LDA(At, 1, 1); PG8_STAGE(PG8_SB(1, 0), b3, voffB); PG8_STAGE(PG8_SB(1, 1), b3 + hstepB, voffB); PG8_STAGE(PG8_SA(1, 0), a3, voffA);
;             PG8_WAIT_V(8); PG8_WAIT_L(0); PG8_BAR; PG8_MMA(1, 0, At, B0); PG8_MMA(1, 1, At, B1); PG8_BAR; PG8_SCHED;
	s_add_i32 s26, s63, s48
	v_lshl_add_u64 v[238:239], v[238:239], 0, s[68:69]
	s_mov_b32 m0, s26
	ds_read_b128 v[176:179], v190 offset:49152
	ds_read_b128 v[180:183], v190 offset:50176
	ds_read_b128 v[192:195], v190 offset:51200
	ds_read_b128 v[196:199], v190 offset:52224
	ds_read_b128 v[200:203], v190 offset:53248
	ds_read_b128 v[204:207], v190 offset:54272
	ds_read_b128 v[218:221], v190 offset:55296
	ds_read_b128 v[222:225], v190 offset:56320
	global_load_lds_dwordx4 v[238:239], off
	s_add_i32 m0, s26, 0x2000
	s_add_u32 s24, s24, 0x40080
	v_lshl_add_u64 v[238:239], v[240:241], 0, s[68:69]
	s_addc_u32 s25, s25, 0
	s_add_i32 s26, s64, s48
	global_load_lds_dwordx4 v[238:239], off
	v_lshl_add_u64 v[238:239], s[24:25], 0, v[148:149]
	s_mov_b32 m0, s26
	s_nop 0
	global_load_lds_dwordx4 v[238:239], off
	v_lshl_add_u64 v[238:239], s[24:25], 0, v[144:145]
	s_add_i32 m0, s26, 0x2000
	s_nop 0
	global_load_lds_dwordx4 v[238:239], off
	v_lshl_add_u64 v[238:239], s[20:21], 0, v[150:151]
	s_mov_b32 m0, s53
	s_nop 0
	global_load_lds_dwordx4 v[238:239], off
	v_lshl_add_u64 v[238:239], s[20:21], 0, v[146:147]
	s_mov_b32 m0, s54
	s_nop 0
	global_load_lds_dwordx4 v[238:239], off
	s_waitcnt vmcnt(8)
	s_waitcnt lgkmcnt(0)
	s_barrier
	s_setprio 1
	s_waitcnt lgkmcnt(0)
	v_mfma_f32_16x16x32_bf16 v[60:63], v[132:135], v[176:179], v[60:63]
	v_mfma_f32_16x16x32_bf16 v[56:59], v[140:143], v[176:179], v[56:59]
	v_mfma_f32_16x16x32_bf16 v[48:51], v[132:135], v[192:195], v[48:51]
	v_mfma_f32_16x16x32_bf16 v[40:43], v[140:143], v[192:195], v[40:43]
	v_mfma_f32_16x16x32_bf16 v[32:35], v[132:135], v[200:203], v[32:35]
	v_mfma_f32_16x16x32_bf16 v[24:27], v[140:143], v[200:203], v[24:27]
	v_mfma_f32_16x16x32_bf16 v[16:19], v[132:135], v[218:221], v[16:19]
	v_mfma_f32_16x16x32_bf16 v[8:11], v[140:143], v[218:221], v[8:11]
	v_mfma_f32_16x16x32_bf16 v[60:63], v[136:139], v[180:183], v[60:63]
	v_mfma_f32_16x16x32_bf16 v[56:59], v[156:159], v[180:183], v[56:59]
	v_mfma_f32_16x16x32_bf16 v[48:51], v[136:139], v[196:199], v[48:51]
	v_mfma_f32_16x16x32_bf16 v[40:43], v[156:159], v[196:199], v[40:43]
	v_mfma_f32_16x16x32_bf16 v[32:35], v[136:139], v[204:207], v[32:35]
	v_mfma_f32_16x16x32_bf16 v[24:27], v[156:159], v[204:207], v[24:27]
	v_mfma_f32_16x16x32_bf16 v[16:19], v[136:139], v[222:225], v[16:19]
	v_mfma_f32_16x16x32_bf16 v[8:11], v[156:159], v[222:225], v[8:11]
	s_setprio 0
	s_setprio 1
	v_mfma_f32_16x16x32_bf16 v[52:55], v[160:163], v[176:179], v[52:55]
	v_mfma_f32_16x16x32_bf16 v[44:47], v[168:171], v[176:179], v[44:47]
	v_mfma_f32_16x16x32_bf16 v[36:39], v[160:163], v[192:195], v[36:39]
	v_mfma_f32_16x16x32_bf16 v[28:31], v[168:171], v[192:195], v[28:31]
	v_mfma_f32_16x16x32_bf16 v[20:23], v[160:163], v[200:203], v[20:23]
	v_mfma_f32_16x16x32_bf16 v[12:15], v[168:171], v[200:203], v[12:15]
	v_mfma_f32_16x16x32_bf16 v[4:7], v[160:163], v[218:221], v[4:7]
	v_mfma_f32_16x16x32_bf16 v[0:3], v[168:171], v[218:221], v[0:3]
	v_mfma_f32_16x16x32_bf16 v[52:55], v[164:167], v[180:183], v[52:55]
	v_mfma_f32_16x16x32_bf16 v[44:47], v[172:175], v[180:183], v[44:47]
	v_mfma_f32_16x16x32_bf16 v[36:39], v[164:167], v[196:199], v[36:39]
	v_mfma_f32_16x16x32_bf16 v[28:31], v[172:175], v[196:199], v[28:31]
	v_mfma_f32_16x16x32_bf16 v[20:23], v[164:167], v[204:207], v[20:23]
	v_mfma_f32_16x16x32_bf16 v[12:15], v[172:175], v[204:207], v[12:15]
	v_mfma_f32_16x16x32_bf16 v[4:7], v[164:167], v[222:225], v[4:7]
	v_mfma_f32_16x16x32_bf16 v[0:3], v[172:175], v[222:225], v[0:3]
	s_setprio 0
	s_barrier
	s_add_i32 s62, s62, 2
	s_add_u32 s2, s2, 0x100
	s_addc_u32 s3, s3, 0
	s_cmp_gt_u32 s62, 13
	s_cbranch_scc0 .LBB0_702
	s_branch .Lpeel_exit_702

; #define PG8_BAR __builtin_amdgcn_s_barrier()
;     ...
;         if (wr == 0) PG8_BAR;
.Lpeel_exit_702:
	s_and_b64 vcc, exec, s[12:13]
	s_cbranch_vccz .LBB0_705
	s_barrier
